# attention unit epilogues: the eight gate / sub-norm weight loads issued together instead of one per output group behind its own wait
# baseline (speedup 1.0000x reference)
; #define MFMA(a, b, c) __builtin_amdgcn_mfma_f32_32x32x16_bf16((a), (b), (c), 0, 0, 0)
; #define KV_ISSUE(tile_, slot_) do { \
;     const bf16_t* kp_ = kbase + (size_t)(tile_) * 4096 + kvoff; const bf16_t* vp_ = vbase + (size_t)(tile_) * 4096 + kvoff; \
;     char* lp_ = smem + (slot_) * ATT_SLOT + tid * 16; \
;     dma16(kp_, lp_); dma16(kp_ + 2048, lp_ + 4096); dma16(vp_, lp_ + ATT_V); dma16(vp_ + 2048, lp_ + ATT_V + 4096); } while (0)
; template <int KIND>
; DI void attn_unit(const Params& p, int l, int b, int head, int qt, int qcol, int kcol, int vfeat, int gcol, int mixcol,
;                   int t1, int n1, int t2, int n2, char* smem) {
;     ...
;     for (int it = 0; it < nt; ++it) {
;         const int tile = (it < n1) ? t1 + it : t2 + (it - n1);
;         if (it + 1 < nt) asm volatile("s_waitcnt vmcnt(4)" ::: "memory"); else asm volatile("s_waitcnt vmcnt(0)" ::: "memory");
;         __builtin_amdgcn_s_barrier();
;         const char* sk = smem + sc * ATT_SLOT;
;         const char* sv = sk + ATT_V;
;         bool active = true;
;         if (KIND == 2 && tile < 32) active = (tile >= r0w) && (tile < r0w + 8);
;         bf16x8 kf[8], vf[8];
;         if (active) {
; #pragma unroll
;             for (int s = 0; s < 4; ++s)
; #pragma unroll
;                 for (int t = 0; t < 2; ++t) kf[2 * s + t] = *(const bf16x8*)(sk + (32 * t + r) * 128 + (((2 * s + h) ^ xr) << 4));
;         }
;         __builtin_amdgcn_sched_barrier(0);
;         if (it + 2 < nt) { const int nx = (it + 2 < n1) ? t1 + it + 2 : t2 + (it + 2 - n1); KV_ISSUE(nx, sn); }
;         sc = (sc == 2) ? 0 : sc + 1; sn = (sn == 2) ? 0 : sn + 1;
;         __builtin_amdgcn_sched_barrier(0);
;         if (active) {
;     ...
;             if (KIND == 0) {
;                 f32x16 S0[2], S1[2];
; #pragma unroll
;                 for (int t = 0; t < 2; ++t) { S0[t] = MFMA(kf[t], qf[0], cz); S1[t] = MFMA(kf[4 + t], qf[2], cz); }
; #pragma unroll
;                 for (int t = 0; t < 2; ++t) { S0[t] = MFMA(kf[2 + t], qf[1], S0[t]); S1[t] = MFMA(kf[6 + t], qf[3], S1[t]); }
;                 LOAD_VF();
;                 softmax_tile(S0, l0);
;                 pv_tile(S0, O0, vf);
;                 softmax_tile(S1, l1);
;                 pv_tile(S1, O1, vf);
.Lk0u_exit:
	v_add_f32_e32 v252, v80, v252
	v_add_f32_e32 v253, v81, v253
	v_cvt_pk_bf16_f32 v80, v80, v81
	v_add_f32_e32 v252, v82, v252
	v_add_f32_e32 v253, v83, v253
	v_cvt_pk_bf16_f32 v81, v82, v83
	v_add_f32_e32 v252, v84, v252
	v_add_f32_e32 v253, v85, v253
	v_cvt_pk_bf16_f32 v82, v84, v85
	v_add_f32_e32 v252, v86, v252
	v_add_f32_e32 v253, v87, v253
	v_cvt_pk_bf16_f32 v83, v86, v87
	v_add_f32_e32 v252, v88, v252
	v_add_f32_e32 v253, v89, v253
	v_cvt_pk_bf16_f32 v88, v88, v89
	v_add_f32_e32 v252, v90, v252
	v_add_f32_e32 v253, v91, v253
	v_cvt_pk_bf16_f32 v89, v90, v91
	v_add_f32_e32 v252, v92, v252
	v_add_f32_e32 v253, v93, v253
	v_cvt_pk_bf16_f32 v90, v92, v93
	v_add_f32_e32 v252, v94, v252
	v_add_f32_e32 v253, v95, v253
	v_cvt_pk_bf16_f32 v91, v94, v95
	v_add_f32_e32 v252, v252, v253
	v_add_f32_e32 v194, v194, v252
	v_mfma_f32_32x32x16_bf16 v[64:79], v[188:191], v[96:99], v[64:79]
	v_mfma_f32_32x32x16_bf16 v[16:31], v[184:187], v[96:99], v[16:31]
	v_mfma_f32_32x32x16_bf16 v[64:79], v[180:183], v[104:107], v[64:79]
	v_mfma_f32_32x32x16_bf16 v[16:31], v[176:179], v[104:107], v[16:31]
	v_mfma_f32_32x32x16_bf16 v[64:79], v[172:175], v[80:83], v[64:79]
	v_mfma_f32_32x32x16_bf16 v[16:31], v[168:171], v[80:83], v[16:31]
	v_mfma_f32_32x32x16_bf16 v[64:79], v[164:167], v[88:91], v[64:79]
	v_mfma_f32_32x32x16_bf16 v[16:31], v[160:163], v[88:91], v[16:31]
	s_lshl_b32 s4, s35, 14
	s_add_i32 s5, s4, 32
	v_add_u32_e32 v92, s5, v217
	v_add_u32_e32 v180, v92, v219
	v_add_u32_e32 v196, v92, v218
	v_add_u32_e32 v197, v92, v216
	v_add_u32_e32 v198, v92, v215
	s_waitcnt vmcnt(4)
	s_barrier
	ds_read_b128 v[80:83], v180
	ds_read_b128 v[84:87], v180 offset:4096
	ds_read_b128 v[160:163], v196
	ds_read_b128 v[164:167], v196 offset:4096
	ds_read_b128 v[88:91], v197
	ds_read_b128 v[168:171], v197 offset:4096
	ds_read_b128 v[172:175], v198
	ds_read_b128 v[176:179], v198 offset:4096
	s_waitcnt lgkmcnt(0)
	v_mfma_f32_32x32x16_bf16 v[128:143], v[80:83], v[152:155], v[0:15]
	v_mfma_f32_32x32x16_bf16 v[96:111], v[88:91], v[156:159], v[0:15]
	v_mfma_f32_32x32x16_bf16 v[112:127], v[84:87], v[152:155], v[0:15]
	v_mfma_f32_32x32x16_bf16 v[80:95], v[168:171], v[156:159], v[0:15]
	v_mfma_f32_32x32x16_bf16 v[128:143], v[160:163], v[144:147], v[128:143]
	v_mfma_f32_32x32x16_bf16 v[96:111], v[172:175], v[148:151], v[96:111]
	v_mfma_f32_32x32x16_bf16 v[112:127], v[164:167], v[144:147], v[112:127]
	v_mfma_f32_32x32x16_bf16 v[80:95], v[176:179], v[148:151], v[80:95]
	ds_read_b128 v[188:191], v180 offset:8192
	ds_read_b128 v[184:187], v180 offset:12288
	ds_read_b128 v[180:183], v196 offset:8192
	ds_read_b128 v[176:179], v196 offset:12288
	ds_read_b128 v[172:175], v197 offset:8192
	ds_read_b128 v[168:171], v197 offset:12288
	ds_read_b128 v[164:167], v198 offset:8192
	ds_read_b128 v[160:163], v198 offset:12288
	s_nop 0
	v_exp_f32_e32 v128, v128
	v_exp_f32_e32 v129, v129
	v_exp_f32_e32 v130, v130
	v_exp_f32_e32 v131, v131
	v_exp_f32_e32 v132, v132
	v_exp_f32_e32 v133, v133
	v_exp_f32_e32 v134, v134
	v_exp_f32_e32 v135, v135
	v_add_f32_e64 v196, v128, 0
	v_add_f32_e64 v197, v129, 0
	v_cvt_pk_bf16_f32 v128, v128, v129
	v_add_f32_e64 v196, v130, v196
	v_add_f32_e64 v197, v131, v197
	v_cvt_pk_bf16_f32 v129, v130, v131
	v_cvt_pk_bf16_f32 v130, v132, v133
	v_cvt_pk_bf16_f32 v131, v134, v135
	v_add_f32_e64 v196, v132, v196
	v_add_f32_e64 v197, v133, v197
	v_exp_f32_e32 v136, v136
	s_waitcnt lgkmcnt(0)
	v_mfma_f32_32x32x16_bf16 v[48:63], v[188:191], v[128:131], v[48:63]
	v_exp_f32_e32 v137, v137
	v_exp_f32_e32 v138, v138
	v_exp_f32_e32 v139, v139
	v_exp_f32_e32 v132, v140
	v_exp_f32_e32 v133, v141
	v_exp_f32_e32 v140, v142
	v_exp_f32_e32 v141, v143
	v_mfma_f32_32x32x16_bf16 v[32:47], v[184:187], v[128:131], v[32:47]
	v_add_f32_e64 v134, v134, v196
	v_add_f32_e64 v135, v135, v197
	v_cvt_pk_bf16_f32 v128, v136, v137
	v_cvt_pk_bf16_f32 v129, v138, v139
	v_cvt_pk_bf16_f32 v130, v132, v133
	v_cvt_pk_bf16_f32 v131, v140, v141
	v_add_f32_e64 v134, v136, v134
	v_add_f32_e64 v135, v137, v135
	v_exp_f32_e32 v112, v112
	v_mfma_f32_32x32x16_bf16 v[48:63], v[180:183], v[128:131], v[48:63]
	v_add_f32_e64 v134, v138, v134
	v_add_f32_e64 v135, v139, v135
	v_exp_f32_e32 v113, v113
	v_add_f32_e64 v134, v132, v134
	v_add_f32_e64 v135, v133, v135
	v_exp_f32_e32 v116, v116
	v_add_f32_e64 v132, v140, v134
	v_add_f32_e64 v133, v141, v135
	v_exp_f32_e32 v134, v114
	v_exp_f32_e32 v135, v115
	v_mfma_f32_32x32x16_bf16 v[32:47], v[176:179], v[128:131], v[32:47]
	v_exp_f32_e32 v117, v117
	v_exp_f32_e32 v118, v118
	v_exp_f32_e32 v119, v119
	v_add_f32_e64 v132, v112, v132
	v_add_f32_e64 v133, v113, v133
	v_cvt_pk_bf16_f32 v112, v112, v113
	v_cvt_pk_bf16_f32 v113, v134, v135
	v_cvt_pk_bf16_f32 v114, v116, v117
	v_cvt_pk_bf16_f32 v115, v118, v119
	v_add_f32_e64 v128, v134, v132
	v_add_f32_e64 v129, v135, v133
	v_exp_f32_e32 v120, v120
	v_mfma_f32_32x32x16_bf16 v[48:63], v[172:175], v[112:115], v[48:63]
	v_add_f32_e64 v116, v116, v128
	v_add_f32_e64 v117, v117, v129
	v_exp_f32_e32 v121, v121
	v_add_f32_e64 v116, v118, v116
	v_add_f32_e64 v117, v119, v117
	v_exp_f32_e32 v118, v122
	v_exp_f32_e32 v119, v123
	v_exp_f32_e32 v122, v124
	v_exp_f32_e32 v123, v125
	v_mfma_f32_32x32x16_bf16 v[32:47], v[168:171], v[112:115], v[32:47]
	v_exp_f32_e32 v124, v126
	v_exp_f32_e32 v125, v127
	v_exp_f32_e32 v96, v96
	v_exp_f32_e32 v97, v97
	v_exp_f32_e32 v98, v98
	v_exp_f32_e32 v99, v99
	v_exp_f32_e32 v100, v100
	v_exp_f32_e32 v101, v101
	v_exp_f32_e32 v102, v102
	v_exp_f32_e32 v103, v103
	v_cvt_pk_bf16_f32 v112, v120, v121
	v_cvt_pk_bf16_f32 v113, v118, v119
	v_cvt_pk_bf16_f32 v114, v122, v123
	v_cvt_pk_bf16_f32 v115, v124, v125
; #define MFMA(a, b, c) __builtin_amdgcn_mfma_f32_32x32x16_bf16((a), (b), (c), 0, 0, 0)
; #define KV_ISSUE(tile_, slot_) do { \
;     const bf16_t* kp_ = kbase + (size_t)(tile_) * 4096 + kvoff; const bf16_t* vp_ = vbase + (size_t)(tile_) * 4096 + kvoff; \
;     char* lp_ = smem + (slot_) * ATT_SLOT + tid * 16; \
;     dma16(kp_, lp_); dma16(kp_ + 2048, lp_ + 4096); dma16(vp_, lp_ + ATT_V); dma16(vp_ + 2048, lp_ + ATT_V + 4096); } while (0)
; template <int KIND>
; DI void attn_unit(const Params& p, int l, int b, int head, int qt, int qcol, int kcol, int vfeat, int gcol, int mixcol,
;                   int t1, int n1, int t2, int n2, char* smem) {
;     ...
;     for (int it = 0; it < nt; ++it) {
;         const int tile = (it < n1) ? t1 + it : t2 + (it - n1);
;         if (it + 1 < nt) asm volatile("s_waitcnt vmcnt(4)" ::: "memory"); else asm volatile("s_waitcnt vmcnt(0)" ::: "memory");
;         __builtin_amdgcn_s_barrier();
;         const char* sk = smem + sc * ATT_SLOT;
;         const char* sv = sk + ATT_V;
;         bool active = true;
;         if (KIND == 2 && tile < 32) active = (tile >= r0w) && (tile < r0w + 8);
;         bf16x8 kf[8], vf[8];
;         if (active) {
; #pragma unroll
;             for (int s = 0; s < 4; ++s)
; #pragma unroll
;                 for (int t = 0; t < 2; ++t) kf[2 * s + t] = *(const bf16x8*)(sk + (32 * t + r) * 128 + (((2 * s + h) ^ xr) << 4));
;         }
;         __builtin_amdgcn_sched_barrier(0);
;         if (it + 2 < nt) { const int nx = (it + 2 < n1) ? t1 + it + 2 : t2 + (it + 2 - n1); KV_ISSUE(nx, sn); }
;         sc = (sc == 2) ? 0 : sc + 1; sn = (sn == 2) ? 0 : sn + 1;
;         __builtin_amdgcn_sched_barrier(0);
;         if (active) {
;     ...
;             if (KIND == 0) {
;                 f32x16 S0[2], S1[2];
; #pragma unroll
;                 for (int t = 0; t < 2; ++t) { S0[t] = MFMA(kf[t], qf[0], cz); S1[t] = MFMA(kf[4 + t], qf[2], cz); }
; #pragma unroll
;                 for (int t = 0; t < 2; ++t) { S0[t] = MFMA(kf[2 + t], qf[1], S0[t]); S1[t] = MFMA(kf[6 + t], qf[3], S1[t]); }
;                 LOAD_VF();
;                 softmax_tile(S0, l0);
;                 pv_tile(S0, O0, vf);
;                 softmax_tile(S1, l1);
;                 pv_tile(S1, O1, vf);
	v_exp_f32_e32 v104, v104
	v_exp_f32_e32 v105, v105
	v_mfma_f32_32x32x16_bf16 v[48:63], v[164:167], v[112:115], v[48:63]
	v_exp_f32_e32 v106, v106
	v_exp_f32_e32 v107, v107
	v_exp_f32_e32 v80, v80
	v_exp_f32_e32 v81, v81
	v_exp_f32_e32 v82, v82
	v_exp_f32_e32 v83, v83
	v_exp_f32_e32 v84, v84
	v_mfma_f32_32x32x16_bf16 v[32:47], v[160:163], v[112:115], v[32:47]
	v_add_f32_e64 v112, v96, 0
	v_add_f32_e64 v113, v97, 0
	v_cvt_pk_bf16_f32 v96, v96, v97
	v_add_f32_e64 v112, v98, v112
	v_add_f32_e64 v113, v99, v113
	v_cvt_pk_bf16_f32 v97, v98, v99
	v_cvt_pk_bf16_f32 v98, v100, v101
	v_cvt_pk_bf16_f32 v99, v102, v103
	v_add_f32_e64 v112, v100, v112
	v_add_f32_e64 v113, v101, v113
	v_exp_f32_e32 v100, v108
	v_mfma_f32_32x32x16_bf16 v[64:79], v[188:191], v[96:99], v[64:79]
	v_exp_f32_e32 v101, v109
	v_add_f32_e64 v112, v102, v112
	v_add_f32_e64 v113, v103, v113
	v_exp_f32_e32 v102, v110
	v_exp_f32_e32 v103, v111
	v_add_f32_e64 v112, v104, v112
	v_add_f32_e64 v113, v105, v113
	v_exp_f32_e32 v85, v85
	v_add_f32_e64 v112, v106, v112
	v_add_f32_e64 v113, v107, v113
	v_mfma_f32_32x32x16_bf16 v[16:31], v[184:187], v[96:99], v[16:31]
	v_add_f32_e64 v108, v100, v112
	v_add_f32_e64 v109, v101, v113
	v_cvt_pk_bf16_f32 v98, v100, v101
	v_add_f32_e64 v96, v102, v108
	v_add_f32_e64 v97, v103, v109
	v_cvt_pk_bf16_f32 v99, v102, v103
	v_add_f32_e64 v108, v80, v96
	v_add_f32_e64 v109, v81, v97
	v_cvt_pk_bf16_f32 v96, v104, v105
	v_cvt_pk_bf16_f32 v97, v106, v107
	v_exp_f32_e32 v86, v86
	v_exp_f32_e32 v87, v87
	v_mfma_f32_32x32x16_bf16 v[64:79], v[180:183], v[96:99], v[64:79]
	v_add_f32_e64 v100, v82, v108
	v_add_f32_e64 v101, v83, v109
	v_exp_f32_e32 v88, v88
	v_add_f32_e64 v100, v84, v100
	v_add_f32_e64 v101, v85, v101
	v_exp_f32_e32 v89, v89
	v_cvt_pk_bf16_f32 v80, v80, v81
	v_cvt_pk_bf16_f32 v81, v82, v83
	v_cvt_pk_bf16_f32 v82, v84, v85
	v_mfma_f32_32x32x16_bf16 v[16:31], v[176:179], v[96:99], v[16:31]
	v_cvt_pk_bf16_f32 v83, v86, v87
	v_add_f32_e64 v96, v86, v100
	v_add_f32_e64 v97, v87, v101
	v_exp_f32_e32 v86, v90
	v_exp_f32_e32 v87, v91
	v_exp_f32_e32 v90, v92
	v_exp_f32_e32 v91, v93
	v_exp_f32_e32 v92, v94
	v_mfma_f32_32x32x16_bf16 v[64:79], v[172:175], v[80:83], v[64:79]
	v_exp_f32_e32 v93, v95
	s_addk_i32 s4, 0x4000
	v_add_f32_e64 v84, v88, v96
	v_add_f32_e64 v85, v89, v97
	s_cmp_lg_u32 s35, 2
	s_cselect_b32 s4, s4, 0
	s_add_i32 s4, s4, 32
	s_waitcnt vmcnt(0)
	v_mfma_f32_32x32x16_bf16 v[16:31], v[168:171], v[80:83], v[16:31]
	v_add_f32_e64 v80, v86, v84
	v_add_f32_e64 v81, v87, v85
	v_cvt_pk_bf16_f32 v82, v90, v91
	v_add_f32_e64 v80, v90, v80
	v_add_f32_e64 v81, v91, v81
	v_cvt_pk_bf16_f32 v83, v92, v93
	v_add_f32_e64 v168, v92, v80
	v_add_f32_e64 v169, v93, v81
	v_cvt_pk_bf16_f32 v80, v88, v89
	v_add_u32_e32 v88, s4, v217
	v_cvt_pk_bf16_f32 v81, v86, v87
	v_add_u32_e32 v174, v88, v219
	v_add_u32_e32 v175, v88, v218
	v_add_u32_e32 v176, v88, v216
	v_add_u32_e32 v177, v88, v215
	v_mfma_f32_32x32x16_bf16 v[64:79], v[164:167], v[80:83], v[64:79]
	s_barrier
	ds_read_b128 v[84:87], v174
	ds_read_b128 v[128:131], v174 offset:4096
	ds_read_b128 v[132:135], v175
	ds_read_b128 v[136:139], v175 offset:4096
	ds_read_b128 v[96:99], v176
	ds_read_b128 v[140:143], v176 offset:4096
	ds_read_b128 v[164:167], v177
	ds_read_b128 v[170:173], v177 offset:4096
	v_add_f32_e64 v116, v120, v116
	v_add_f32_e64 v117, v121, v117
	s_nop 0
	v_add_f32_e64 v116, v118, v116
	v_add_f32_e64 v117, v119, v117
	v_mfma_f32_32x32x16_bf16 v[16:31], v[160:163], v[80:83], v[16:31]
	v_add_f32_e64 v116, v122, v116
	v_add_f32_e64 v117, v123, v117
	v_add_f32_e64 v196, v124, v116
	v_add_f32_e64 v197, v125, v117
	s_waitcnt lgkmcnt(0)
	v_mfma_f32_32x32x16_bf16 v[112:127], v[84:87], v[152:155], v[0:15]
	v_mfma_f32_32x32x16_bf16 v[80:95], v[96:99], v[156:159], v[0:15]
	v_mfma_f32_32x32x16_bf16 v[96:111], v[128:131], v[152:155], v[0:15]
	v_mfma_f32_32x32x16_bf16 v[0:15], v[140:143], v[156:159], v[0:15]
	v_mfma_f32_32x32x16_bf16 v[112:127], v[132:135], v[144:147], v[112:127]
	v_mfma_f32_32x32x16_bf16 v[80:95], v[164:167], v[148:151], v[80:95]
	v_mfma_f32_32x32x16_bf16 v[96:111], v[136:139], v[144:147], v[96:111]
	v_mfma_f32_32x32x16_bf16 v[0:15], v[170:173], v[148:151], v[0:15]
	ds_read_b128 v[156:159], v174 offset:8192
	ds_read_b128 v[152:155], v174 offset:12288
	ds_read_b128 v[148:151], v175 offset:8192
	ds_read_b128 v[144:147], v175 offset:12288
	ds_read_b128 v[140:143], v176 offset:8192
	ds_read_b128 v[136:139], v176 offset:12288
	ds_read_b128 v[132:135], v177 offset:8192
	ds_read_b128 v[128:131], v177 offset:12288
	s_nop 0
	v_exp_f32_e32 v112, v112
	v_exp_f32_e32 v113, v113
	v_exp_f32_e32 v114, v114
	v_exp_f32_e32 v115, v115
	v_exp_f32_e32 v116, v116
	v_exp_f32_e32 v117, v117
	v_exp_f32_e32 v118, v118
	v_exp_f32_e32 v119, v119
	v_add_f32_e64 v160, v112, 0
	v_add_f32_e64 v161, v113, 0
	v_cvt_pk_bf16_f32 v112, v112, v113
	v_add_f32_e64 v160, v114, v160
	v_add_f32_e64 v161, v115, v161
	v_cvt_pk_bf16_f32 v113, v114, v115
	v_cvt_pk_bf16_f32 v114, v116, v117
	v_cvt_pk_bf16_f32 v115, v118, v119
	v_exp_f32_e32 v120, v120
	v_exp_f32_e32 v121, v121
	s_waitcnt lgkmcnt(0)
; #define MFMA(a, b, c) __builtin_amdgcn_mfma_f32_32x32x16_bf16((a), (b), (c), 0, 0, 0)
; DI int otid() { int t = threadIdx.x; asm volatile("" : "+v"(t)); return t; }
; DI float xsum32(float x) { const unsigned u = __float_as_uint(x); const auto r2 = __builtin_amdgcn_permlane32_swap(u, u, false, false); return __uint_as_float(r2[0]) + __uint_as_float(r2[1]); }
; #define LOAD_VF() do { \
;             __builtin_amdgcn_sched_barrier(0); \
;             _Pragma("unroll") for (int s = 0; s < 4; ++s) \
;                 _Pragma("unroll") for (int dt = 0; dt < 2; ++dt) vf[2 * s + dt] = ldv_frag(sv, 32 * dt + r, 2 * s + h, xr); \
;             __builtin_amdgcn_sched_barrier(0); } while (0)
; template <int KIND>
; DI void attn_unit(const Params& p, int l, int b, int head, int qt, int qcol, int kcol, int vfeat, int gcol, int mixcol,
;                   int t1, int n1, int t2, int n2, char* smem) {
;     ...
;                 softmax_tile(S0, l0);
;                 pv_tile(S0, O0, vf);
;                 softmax_tile(S1, l1);
;                 pv_tile(S1, O1, vf);
;             } else {
;                 f32x16 S[2];
; #pragma unroll
;                 for (int t = 0; t < 2; ++t) S[t] = MFMA(kf[t], qf[0], cz);
; #pragma unroll
;                 for (int s = 1; s < 4; ++s)
; #pragma unroll
;                     for (int t = 0; t < 2; ++t) S[t] = MFMA(kf[2 * s + t], qf[s], S[t]);
;                 LOAD_VF();
;                 if (KIND == 2 && tile < 32) {
;                     const char* brow = smem + ATT_BIAS + (tile - nrow + 7) * 128;
; #pragma unroll
;                     for (int t = 0; t < 2; ++t)
; #pragma unroll
;                         for (int e = 0; e < 16; ++e) S[t][e] += *(const float*)(brow + bcol[t][e]);
;                 }
;                 softmax_tile(S, l0);
;                 pv_tile(S, O0, vf);
;             }
;     ...
;         }
;     }
;     l0 = xsum32(l0);
;     const float inv0 = 1.f / l0;
;     const int tid_e = otid();
;     const size_t qrow_e = (size_t)b * TPB + qt * 128 + 32 * (tid_e >> 6) + (tid_e & 31);
;     bf16_t* orow = p.hmix + ((size_t)(mixcol >> 5) * NTOK + qrow_e) * 32;
;     const bf16_t* grow = p.qkv + ((size_t)(gcol >> 6) * NTOK + qrow_e) * 64;
;     if (KIND == 0) {
;         l1 = xsum32(l1);
;         const float lam = p.lam[l];
;         const float inv1 = lam / l1;
	v_mfma_f32_32x32x16_bf16 v[48:63], v[156:159], v[112:115], v[48:63]
	v_exp_f32_e32 v122, v122
	v_exp_f32_e32 v123, v123
	v_exp_f32_e32 v124, v124
	v_exp_f32_e32 v125, v125
	v_exp_f32_e32 v126, v126
	v_exp_f32_e32 v127, v127
	v_add_f32_e64 v160, v116, v160
	v_add_f32_e64 v161, v117, v161
	v_mfma_f32_32x32x16_bf16 v[32:47], v[152:155], v[112:115], v[32:47]
	v_add_f32_e64 v160, v118, v160
	v_add_f32_e64 v161, v119, v161
	v_exp_f32_e32 v118, v96
	v_add_f32_e64 v160, v120, v160
	v_add_f32_e64 v161, v121, v161
	v_exp_f32_e32 v119, v97
	v_add_f32_e64 v116, v122, v160
	v_add_f32_e64 v117, v123, v161
	v_exp_f32_e32 v160, v98
	v_exp_f32_e32 v161, v99
	v_cvt_pk_bf16_f32 v96, v120, v121
	v_cvt_pk_bf16_f32 v97, v122, v123
	v_cvt_pk_bf16_f32 v98, v124, v125
	v_cvt_pk_bf16_f32 v99, v126, v127
	v_add_f32_e64 v116, v124, v116
	v_add_f32_e64 v117, v125, v117
	v_exp_f32_e32 v100, v100
	v_mfma_f32_32x32x16_bf16 v[48:63], v[148:151], v[96:99], v[48:63]
	v_exp_f32_e32 v101, v101
	v_add_f32_e64 v116, v126, v116
	v_add_f32_e64 v117, v127, v117
	v_exp_f32_e32 v102, v102
	v_exp_f32_e32 v103, v103
	v_add_f32_e64 v112, v118, v116
	v_add_f32_e64 v113, v119, v117
	v_exp_f32_e32 v104, v104
	v_exp_f32_e32 v105, v105
	v_mfma_f32_32x32x16_bf16 v[32:47], v[144:147], v[96:99], v[32:47]
	v_add_f32_e64 v112, v160, v112
	v_add_f32_e64 v113, v161, v113
	v_exp_f32_e32 v106, v106
	v_exp_f32_e32 v107, v107
	v_add_f32_e64 v112, v100, v112
	v_add_f32_e64 v113, v101, v113
	v_exp_f32_e32 v108, v108
	v_add_f32_e64 v112, v102, v112
	v_add_f32_e64 v113, v103, v113
	v_cvt_pk_bf16_f32 v96, v118, v119
	v_cvt_pk_bf16_f32 v97, v160, v161
	v_cvt_pk_bf16_f32 v98, v100, v101
	v_cvt_pk_bf16_f32 v99, v102, v103
	v_exp_f32_e32 v109, v109
	v_exp_f32_e32 v100, v110
	v_mfma_f32_32x32x16_bf16 v[48:63], v[140:143], v[96:99], v[48:63]
	v_exp_f32_e32 v101, v111
	v_add_f32_e64 v102, v104, v112
	v_add_f32_e64 v103, v105, v113
	v_exp_f32_e32 v84, v84
	v_add_f32_e64 v102, v106, v102
	v_add_f32_e64 v103, v107, v103
	v_exp_f32_e32 v85, v85
	v_add_f32_e64 v102, v108, v102
	v_add_f32_e64 v103, v109, v103
	v_exp_f32_e32 v86, v86
	v_mfma_f32_32x32x16_bf16 v[32:47], v[136:139], v[96:99], v[32:47]
	v_cvt_pk_bf16_f32 v96, v104, v105
	v_exp_f32_e32 v104, v80
	v_exp_f32_e32 v105, v81
	v_cvt_pk_bf16_f32 v97, v106, v107
	v_exp_f32_e32 v106, v82
	v_exp_f32_e32 v107, v83
	v_exp_f32_e32 v87, v87
	v_add_f32_e64 v102, v100, v102
	v_add_f32_e64 v103, v101, v103
	v_add_f32_e64 v82, v104, 0
	v_add_f32_e64 v83, v105, 0
	v_exp_f32_e32 v88, v88
	v_exp_f32_e32 v89, v89
	v_mov_b32_e32 v110, v196
	v_mov_b32_e32 v111, v102
	v_mov_b32_e32 v102, v197
	v_add_f32_e64 v82, v106, v82
	v_add_f32_e64 v83, v107, v83
	v_exp_f32_e32 v90, v90
	v_exp_f32_e32 v91, v91
	v_cvt_pk_bf16_f32 v99, v100, v101
	v_add_f32_e64 v100, v110, v102
	v_add_f32_e64 v101, v111, v103
	v_add_f32_e64 v82, v84, v82
	v_add_f32_e64 v83, v85, v83
	v_exp_f32_e32 v92, v92
	v_exp_f32_e32 v93, v93
	s_add_u32 s7, s29, s7
	v_pk_add_f32 v[102:103], v[194:195], v[100:101] op_sel:[1,0] op_sel_hi:[0,1]
	v_add_f32_e64 v82, v86, v82
	v_add_f32_e64 v83, v87, v83
	s_addc_u32 s9, s9, 0
	s_add_i32 s8, s8, 0x36000
	s_lshl_b64 s[4:5], s[60:61], 2
	v_cvt_pk_bf16_f32 v98, v108, v109
	v_pk_add_f32 v[80:81], v[102:103], v[100:101] op_sel:[0,1] op_sel_hi:[1,0]
	v_add_f32_e64 v82, v88, v82
	v_add_f32_e64 v83, v89, v83
	s_add_u32 s4, s50, s4
	v_mfma_f32_32x32x16_bf16 v[48:63], v[132:135], v[96:99], v[48:63]
	v_mov_b32_e32 v81, v200
	s_addc_u32 s5, s51, s5
	v_cvt_pk_bf16_f32 v84, v84, v85
	v_cvt_pk_bf16_f32 v85, v86, v87
	v_exp_f32_e32 v94, v94
	v_exp_f32_e32 v95, v95
	v_mfma_f32_32x32x16_bf16 v[32:47], v[128:131], v[96:99], v[32:47]
	v_add_f32_e64 v96, v90, v82
	v_add_f32_e64 v97, v91, v83
	v_exp_f32_e32 v98, v0
	v_exp_f32_e32 v99, v1
	v_add_f32_e64 v0, v92, v96
	v_add_f32_e64 v1, v93, v97
	global_load_dword v96, v193, s[4:5]
	v_cvt_pk_bf16_f32 v82, v104, v105
	v_cvt_pk_bf16_f32 v83, v106, v107
	v_exp_f32_e32 v100, v2
	v_exp_f32_e32 v101, v3
	v_mfma_f32_32x32x16_bf16 v[64:79], v[156:159], v[82:85], v[64:79]
	v_exp_f32_e32 v86, v4
	v_exp_f32_e32 v87, v5
	v_cvt_pk_bf16_f32 v2, v88, v89
	v_cvt_pk_bf16_f32 v3, v90, v91
	v_cvt_pk_bf16_f32 v4, v92, v93
	v_cvt_pk_bf16_f32 v5, v94, v95
	v_add_f32_e64 v0, v94, v0
	v_add_f32_e64 v1, v95, v1
	v_mfma_f32_32x32x16_bf16 v[16:31], v[152:155], v[82:85], v[16:31]
	v_exp_f32_e32 v6, v6
	v_exp_f32_e32 v7, v7
	v_add_f32_e64 v0, v98, v0
	v_add_f32_e64 v1, v99, v1
	v_exp_f32_e32 v8, v8
	v_exp_f32_e32 v9, v9
	v_add_f32_e64 v0, v100, v0
	v_add_f32_e64 v1, v101, v1
	v_exp_f32_e32 v10, v10
	v_mfma_f32_32x32x16_bf16 v[64:79], v[148:151], v[2:5], v[64:79]
	v_exp_f32_e32 v11, v11
	v_add_f32_e64 v82, v86, v0
	v_add_f32_e64 v83, v87, v1
	v_exp_f32_e32 v12, v12
	v_exp_f32_e32 v13, v13
	v_add_f32_e64 v82, v6, v82
	v_add_f32_e64 v83, v7, v83
	v_ashrrev_i32_e32 v0, 1, v81
	v_and_b32_e32 v0, 0xffffffe0, v0
	v_mfma_f32_32x32x16_bf16 v[16:31], v[144:147], v[2:5], v[16:31]
	v_cvt_pk_bf16_f32 v5, v6, v7
	v_exp_f32_e32 v6, v14
	v_exp_f32_e32 v7, v15
	v_add_f32_e64 v14, v8, v82
	v_add_f32_e64 v15, v9, v83
	v_cvt_pk_bf16_f32 v2, v98, v99
	v_add_f32_e64 v14, v10, v14
	v_add_f32_e64 v15, v11, v15
	v_cvt_pk_bf16_f32 v3, v100, v101
	v_cvt_pk_bf16_f32 v4, v86, v87
	v_add_f32_e64 v14, v12, v14
	v_add_f32_e64 v15, v13, v15
	v_ashrrev_i32_e32 v1, 31, v0
	v_mfma_f32_32x32x16_bf16 v[64:79], v[140:143], v[2:5], v[64:79]
	v_add_f32_e64 v14, v6, v14
	v_add_f32_e64 v15, v7, v15
	v_and_or_b32 v84, v81, 31, s7
	v_mov_b32_e32 v85, s9
	v_lshl_add_u64 v[84:85], v[84:85], 0, v[0:1]
	s_mov_b32 s9, s75
	v_lshl_add_u64 v[0:1], v[84:85], 0, s[8:9]
	v_mov_b32_e32 v82, v168
	v_mfma_f32_32x32x16_bf16 v[16:31], v[136:139], v[2:5], v[16:31]
	v_cvt_pk_bf16_f32 v5, v6, v7
	v_mov_b32_e32 v6, v80
	s_nop 1
	v_permlane32_swap_b32_e32 v80, v6
	v_cvt_pk_bf16_f32 v2, v8, v9
	v_add_f32_e32 v8, v80, v6
	v_div_scale_f32 v9, s[8:9], v8, v8, 1.0
	v_cvt_pk_bf16_f32 v3, v10, v11
	v_rcp_f32_e32 v10, v9
	v_cvt_pk_bf16_f32 v4, v12, v13
	v_mov_b32_e32 v83, v14
	v_mov_b32_e32 v14, v169
	v_mfma_f32_32x32x16_bf16 v[64:79], v[132:135], v[2:5], v[64:79]
	v_add_f32_e64 v14, v82, v14
	v_add_f32_e64 v15, v83, v15
	global_load_dword v80, v193, s[4:5] offset:16
	v_add_f32_e64 v6, v194, v14
	v_add_f32_e64 v7, v195, v15
	v_lshlrev_b64 v[0:1], 7, v[0:1]
	v_pk_add_f32 v[6:7], v[6:7], v[14:15] op_sel:[0,1] op_sel_hi:[1,0]
	v_lshl_add_u64 v[0:1], s[40:41], 0, v[0:1]
	v_lshlrev_b32_e32 v88, 3, v214
	v_mfma_f32_32x32x16_bf16 v[16:31], v[128:131], v[2:5], v[16:31]
	v_fma_f32 v2, -v9, v10, 1.0
	v_fmac_f32_e32 v10, v2, v10
	v_div_scale_f32 v2, vcc, 1.0, v8, 1.0
	v_mul_f32_e32 v3, v2, v10
	v_fma_f32 v4, -v9, v3, v2
	v_fmac_f32_e32 v3, v4, v10
	v_fma_f32 v2, -v9, v3, v2
	v_div_fmas_f32 v2, v2, v10, v3
	v_div_fixup_f32 v8, v2, v8, 1.0
	v_mov_b32_e32 v2, v6
	s_nop 1
	v_permlane32_swap_b32_e32 v6, v2
	v_add_f32_e32 v4, v6, v2
	s_waitcnt vmcnt(0)
; DI int otid() { int t = threadIdx.x; asm volatile("" : "+v"(t)); return t; }
; DI float xsum32(float x) { const unsigned u = __float_as_uint(x); const auto r2 = __builtin_amdgcn_permlane32_swap(u, u, false, false); return __uint_as_float(r2[0]) + __uint_as_float(r2[1]); }
; template <int KIND>
; DI void attn_unit(const Params& p, int l, int b, int head, int qt, int qcol, int kcol, int vfeat, int gcol, int mixcol,
;                   int t1, int n1, int t2, int n2, char* smem) {
;     ...
;     l0 = xsum32(l0);
;     const float inv0 = 1.f / l0;
;     const int tid_e = otid();
;     const size_t qrow_e = (size_t)b * TPB + qt * 128 + 32 * (tid_e >> 6) + (tid_e & 31);
;     bf16_t* orow = p.hmix + ((size_t)(mixcol >> 5) * NTOK + qrow_e) * 32;
;     const bf16_t* grow = p.qkv + ((size_t)(gcol >> 6) * NTOK + qrow_e) * 64;
;     if (KIND == 0) {
;         l1 = xsum32(l1);
;         const float lam = p.lam[l];
;         const float inv1 = lam / l1;
;         float ss = 0.f;
; #pragma unroll
;         for (int t = 0; t < 2; ++t)
; #pragma unroll
;             for (int e = 0; e < 16; ++e) { const float o = O0[t][e] * inv0 - O1[t][e] * inv1; O0[t][e] = o; ss += o * o; }
;         ss = xsum32(ss);
;         const float rstd = rsqrtf(ss * (1.f / 64.f) + EPS) * p.lam[4 + l];
;         const float* sw = p.subln + l * 64;
; #pragma unroll
;         for (int t = 0; t < 2; ++t)
; #pragma unroll
;             for (int q = 0; q < 4; ++q) {
;                 const int f = 32 * t + 8 * q + 4 * h;
;                 const float4 w4 = *(const float4*)(sw + f);
;                 const uint2 gg = *(const uint2*)(grow + f);
	v_div_scale_f32 v5, s[4:5], v4, v4, v96
	v_rcp_f32_e32 v6, v5
	v_mov_b32_e32 v89, v193
	v_lshl_add_u64 v[0:1], v[0:1], 0, v[88:89]
	s_mul_i32 s6, s6, 0x9000
	v_fma_f32 v7, -v5, v6, 1.0
	s_mov_b32 s7, s75
	v_fmac_f32_e32 v6, v7, v6
	v_div_scale_f32 v7, vcc, v96, v4, v96
	global_load_dwordx2 v[90:91], v[0:1], off
	global_load_dwordx2 v[170:171], v[0:1], off offset:16
	global_load_dwordx2 v[172:173], v[0:1], off offset:32
	global_load_dwordx2 v[174:175], v[0:1], off offset:48
	global_load_dwordx2 v[176:177], v[0:1], off offset:64
	global_load_dwordx2 v[178:179], v[0:1], off offset:80
	global_load_dwordx2 v[180:181], v[0:1], off offset:96
	global_load_dwordx2 v[182:183], v[0:1], off offset:112
	v_lshl_add_u64 v[2:3], v[84:85], 0, s[6:7]
	v_mul_f32_e32 v9, v7, v6
	s_load_dwordx2 s[4:5], s[0:1], 0xb8
	s_load_dwordx2 s[6:7], s[0:1], 0x78
	v_fma_f32 v10, -v5, v9, v7
	v_fmac_f32_e32 v9, v10, v6
	v_fma_f32 v5, -v5, v9, v7
	v_lshlrev_b64 v[2:3], 6, v[2:3]
	v_div_fmas_f32 v5, v5, v6, v9
	v_div_fixup_f32 v10, v5, v4, v96
	s_waitcnt lgkmcnt(0)
	v_lshl_add_u64 v[2:3], s[4:5], 0, v[2:3]
	s_add_u32 s4, s6, s46
	s_addc_u32 s5, s7, s47
	v_pk_mul_f32 v[4:5], v[66:67], v[10:11] op_sel_hi:[1,0]
	v_pk_mul_f32 v[16:17], v[16:17], v[10:11] op_sel_hi:[1,0]
	v_pk_fma_f32 v[14:15], v[50:51], v[8:9], v[4:5] op_sel_hi:[1,0,1] neg_lo:[0,0,1] neg_hi:[0,0,1]
	global_load_dwordx4 v[4:7], v192, s[4:5]
	global_load_dwordx4 v[216:219], v192, s[4:5] offset:32
	global_load_dwordx4 v[220:223], v192, s[4:5] offset:64
	global_load_dwordx4 v[224:227], v192, s[4:5] offset:96
	global_load_dwordx4 v[228:231], v192, s[4:5] offset:128
	global_load_dwordx4 v[232:235], v192, s[4:5] offset:160
	global_load_dwordx4 v[236:239], v192, s[4:5] offset:192
	global_load_dwordx4 v[240:243], v192, s[4:5] offset:224
	v_pk_mul_f32 v[50:51], v[64:65], v[10:11] op_sel_hi:[1,0]
	v_mul_f32_e32 v64, v15, v15
	v_pk_fma_f32 v[48:49], v[48:49], v[8:9], v[50:51] op_sel_hi:[1,0,1] neg_lo:[0,0,1] neg_hi:[0,0,1]
	v_pk_mul_f32 v[18:19], v[18:19], v[10:11] op_sel_hi:[1,0]
	v_mul_f32_e32 v50, v49, v49
	v_pk_fma_f32 v[50:51], v[48:49], v[48:49], v[50:51] op_sel_hi:[1,1,0]
	v_pk_fma_f32 v[16:17], v[32:33], v[8:9], v[16:17] op_sel_hi:[1,0,1] neg_lo:[0,0,1] neg_hi:[0,0,1]
	v_pk_fma_f32 v[50:51], v[14:15], v[14:15], v[50:51]
	v_pk_fma_f32 v[18:19], v[34:35], v[8:9], v[18:19] op_sel_hi:[1,0,1] neg_lo:[0,0,1] neg_hi:[0,0,1]
	v_pk_add_f32 v[50:51], v[64:65], v[50:51] op_sel_hi:[0,1]
	v_pk_mul_f32 v[64:65], v[70:71], v[10:11] op_sel_hi:[1,0]
	v_mul_f32_e32 v34, v17, v17
	v_pk_fma_f32 v[54:55], v[54:55], v[8:9], v[64:65] op_sel_hi:[1,0,1] neg_lo:[0,0,1] neg_hi:[0,0,1]
	v_pk_mul_f32 v[64:65], v[68:69], v[10:11] op_sel_hi:[1,0]
	v_pk_mul_f32 v[20:21], v[20:21], v[10:11] op_sel_hi:[1,0]
	v_pk_fma_f32 v[52:53], v[52:53], v[8:9], v[64:65] op_sel_hi:[1,0,1] neg_lo:[0,0,1] neg_hi:[0,0,1]
	v_pk_fma_f32 v[20:21], v[36:37], v[8:9], v[20:21] op_sel_hi:[1,0,1] neg_lo:[0,0,1] neg_hi:[0,0,1]
	v_pk_fma_f32 v[50:51], v[52:53], v[52:53], v[50:51]
	v_mul_f32_e32 v64, v53, v53
	v_pk_add_f32 v[50:51], v[64:65], v[50:51] op_sel_hi:[0,1]
	v_pk_fma_f32 v[50:51], v[54:55], v[54:55], v[50:51]
	v_mul_f32_e32 v64, v55, v55
	v_pk_add_f32 v[50:51], v[64:65], v[50:51] op_sel_hi:[0,1]
	v_pk_mul_f32 v[64:65], v[74:75], v[10:11] op_sel_hi:[1,0]
	v_pk_mul_f32 v[22:23], v[22:23], v[10:11] op_sel_hi:[1,0]
	v_pk_fma_f32 v[58:59], v[58:59], v[8:9], v[64:65] op_sel_hi:[1,0,1] neg_lo:[0,0,1] neg_hi:[0,0,1]
	v_pk_mul_f32 v[64:65], v[72:73], v[10:11] op_sel_hi:[1,0]
	v_pk_fma_f32 v[22:23], v[38:39], v[8:9], v[22:23] op_sel_hi:[1,0,1] neg_lo:[0,0,1] neg_hi:[0,0,1]
	v_pk_fma_f32 v[56:57], v[56:57], v[8:9], v[64:65] op_sel_hi:[1,0,1] neg_lo:[0,0,1] neg_hi:[0,0,1]
	v_pk_mul_f32 v[24:25], v[24:25], v[10:11] op_sel_hi:[1,0]
	v_pk_fma_f32 v[50:51], v[56:57], v[56:57], v[50:51]
	v_mul_f32_e32 v64, v57, v57
	v_pk_add_f32 v[50:51], v[64:65], v[50:51] op_sel_hi:[0,1]
	v_pk_fma_f32 v[50:51], v[58:59], v[58:59], v[50:51]
	v_mul_f32_e32 v64, v59, v59
	v_pk_add_f32 v[50:51], v[64:65], v[50:51] op_sel_hi:[0,1]
	v_pk_mul_f32 v[64:65], v[78:79], v[10:11] op_sel_hi:[1,0]
	v_pk_fma_f32 v[24:25], v[40:41], v[8:9], v[24:25] op_sel_hi:[1,0,1] neg_lo:[0,0,1] neg_hi:[0,0,1]
	v_pk_fma_f32 v[62:63], v[62:63], v[8:9], v[64:65] op_sel_hi:[1,0,1] neg_lo:[0,0,1] neg_hi:[0,0,1]
	v_pk_mul_f32 v[64:65], v[76:77], v[10:11] op_sel_hi:[1,0]
	v_pk_mul_f32 v[26:27], v[26:27], v[10:11] op_sel_hi:[1,0]
	v_pk_fma_f32 v[60:61], v[60:61], v[8:9], v[64:65] op_sel_hi:[1,0,1] neg_lo:[0,0,1] neg_hi:[0,0,1]
	v_pk_fma_f32 v[26:27], v[42:43], v[8:9], v[26:27] op_sel_hi:[1,0,1] neg_lo:[0,0,1] neg_hi:[0,0,1]
	v_pk_fma_f32 v[50:51], v[60:61], v[60:61], v[50:51]
	v_mul_f32_e32 v64, v61, v61
	v_pk_add_f32 v[50:51], v[64:65], v[50:51] op_sel_hi:[0,1]
	v_pk_fma_f32 v[50:51], v[62:63], v[62:63], v[50:51]
	v_mul_f32_e32 v64, v63, v63
	v_pk_add_f32 v[50:51], v[64:65], v[50:51] op_sel_hi:[0,1]
	v_pk_fma_f32 v[32:33], v[16:17], v[16:17], v[50:51]
	v_pk_mul_f32 v[30:31], v[30:31], v[10:11] op_sel_hi:[1,0]
	v_pk_add_f32 v[32:33], v[34:35], v[32:33] op_sel_hi:[0,1]
	v_pk_fma_f32 v[32:33], v[18:19], v[18:19], v[32:33]
	v_mul_f32_e32 v34, v19, v19
	v_pk_add_f32 v[32:33], v[34:35], v[32:33] op_sel_hi:[0,1]
	v_pk_fma_f32 v[32:33], v[20:21], v[20:21], v[32:33]
	v_mul_f32_e32 v34, v21, v21
	v_pk_add_f32 v[32:33], v[34:35], v[32:33] op_sel_hi:[0,1]
	v_pk_fma_f32 v[32:33], v[22:23], v[22:23], v[32:33]
	v_mul_f32_e32 v34, v23, v23
	v_pk_add_f32 v[32:33], v[34:35], v[32:33] op_sel_hi:[0,1]
	v_pk_fma_f32 v[32:33], v[24:25], v[24:25], v[32:33]
	v_mul_f32_e32 v34, v25, v25
	v_pk_add_f32 v[32:33], v[34:35], v[32:33] op_sel_hi:[0,1]
	v_pk_fma_f32 v[32:33], v[26:27], v[26:27], v[32:33]
	v_mul_f32_e32 v34, v27, v27
	v_pk_mul_f32 v[10:11], v[28:29], v[10:11] op_sel_hi:[1,0]
	v_pk_add_f32 v[32:33], v[34:35], v[32:33] op_sel_hi:[0,1]
	v_pk_fma_f32 v[30:31], v[46:47], v[8:9], v[30:31] op_sel_hi:[1,0,1] neg_lo:[0,0,1] neg_hi:[0,0,1]
	v_pk_fma_f32 v[8:9], v[44:45], v[8:9], v[10:11] op_sel_hi:[1,0,1] neg_lo:[0,0,1] neg_hi:[0,0,1]
	s_waitcnt vmcnt(1)
; DI unsigned pk2(float a, float b) { f2_t v = {a, b}; bf2_t r = __builtin_convertvector(v, bf2_t); return __builtin_bit_cast(unsigned, r); }
; DI float bf2f(bf16_t v) { return __uint_as_float(((unsigned)v) << 16); }
; template <int KIND>
; DI void attn_unit(const Params& p, int l, int b, int head, int qt, int qcol, int kcol, int vfeat, int gcol, int mixcol,
;                   int t1, int n1, int t2, int n2, char* smem) {
;     ...
;         const float* sw = p.subln + l * 64;
; #pragma unroll
;         for (int t = 0; t < 2; ++t)
; #pragma unroll
;             for (int q = 0; q < 4; ++q) {
;                 const int f = 32 * t + 8 * q + 4 * h;
;                 const float4 w4 = *(const float4*)(sw + f);
;                 const uint2 gg = *(const uint2*)(grow + f);
;                 const float g0 = bf2f((bf16_t)(gg.x & 0xffff)), g1 = bf2f((bf16_t)(gg.x >> 16)), g2 = bf2f((bf16_t)(gg.y & 0xffff)), g3 = bf2f((bf16_t)(gg.y >> 16));
;                 uint2 o;
;                 o.x = pk2(O0[t][4 * q + 0] * rstd * w4.x * g0, O0[t][4 * q + 1] * rstd * w4.y * g1);
;                 o.y = pk2(O0[t][4 * q + 2] * rstd * w4.z * g2, O0[t][4 * q + 3] * rstd * w4.w * g3);
;                 *(uint2*)(orow + (size_t)t * NTOK * 32 + 8 * q + 4 * h) = o;
;             }
	v_lshlrev_b32_e32 v12, 16, v90
	v_pk_fma_f32 v[10:11], v[8:9], v[8:9], v[32:33]
	v_mul_f32_e32 v28, v9, v9
	v_pk_add_f32 v[10:11], v[28:29], v[10:11] op_sel_hi:[0,1]
	v_pk_fma_f32 v[10:11], v[30:31], v[30:31], v[10:11]
	v_mul_f32_e32 v28, v31, v31
	v_pk_add_f32 v[10:11], v[28:29], v[10:11] op_sel_hi:[0,1]
	v_mov_b32_e32 v11, v10
	s_nop 1
	v_permlane32_swap_b32_e32 v10, v11
	v_add_f32_e32 v10, v10, v11
	v_fmamk_f32 v10, v10, 0x3c800000, v201
	v_mul_f32_e32 v11, 0x4b800000, v10
	v_cmp_gt_f32_e32 vcc, s87, v10
	v_and_b32_e32 v13, 0xffff0000, v90
	v_lshl_add_u64 v[2:3], v[2:3], 0, v[88:89]
	v_cndmask_b32_e32 v10, v10, v11, vcc
	v_rsq_f32_e32 v28, v10
	v_lshlrev_b32_e32 v10, 16, v91
	v_and_b32_e32 v11, 0xffff0000, v91
	s_mov_b32 s6, 0x120000
	v_mul_f32_e32 v29, 0x45800000, v28
	v_cndmask_b32_e32 v28, v28, v29, vcc
	v_mul_f32_e32 v28, v80, v28
	v_pk_mul_f32 v[32:33], v[48:49], v[28:29] op_sel_hi:[1,0]
	s_waitcnt vmcnt(0)
	v_pk_mul_f32 v[4:5], v[4:5], v[32:33]
	s_nop 0
	v_pk_mul_f32 v[4:5], v[4:5], v[12:13]
	v_pk_mul_f32 v[12:13], v[14:15], v[28:29] op_sel_hi:[1,0]
	v_cvt_pk_bf16_f32 v4, v4, v5
	v_pk_mul_f32 v[6:7], v[6:7], v[12:13]
	v_pk_mul_f32 v[14:15], v[52:53], v[28:29] op_sel_hi:[1,0]
	v_pk_mul_f32 v[6:7], v[6:7], v[10:11]
	s_nop 0
	v_cvt_pk_bf16_f32 v5, v6, v7
	global_store_dwordx2 v[2:3], v[4:5], off
	s_nop 1
	v_mov_b32_e32 v10, v170
	v_mov_b32_e32 v11, v171
	s_nop 0
	s_nop 1
	v_mov_b32_e32 v4, v216
	v_mov_b32_e32 v5, v217
	v_mov_b32_e32 v6, v218
	v_mov_b32_e32 v7, v219
	s_waitcnt vmcnt(1)
	v_lshlrev_b32_e32 v12, 16, v10
	v_and_b32_e32 v13, 0xffff0000, v10
	s_waitcnt vmcnt(0)
	v_pk_mul_f32 v[4:5], v[4:5], v[14:15]
	v_lshlrev_b32_e32 v10, 16, v11
	v_pk_mul_f32 v[4:5], v[4:5], v[12:13]
	v_pk_mul_f32 v[12:13], v[54:55], v[28:29] op_sel_hi:[1,0]
	v_and_b32_e32 v11, 0xffff0000, v11
	v_pk_mul_f32 v[6:7], v[12:13], v[6:7]
	v_cvt_pk_bf16_f32 v4, v4, v5
	v_pk_mul_f32 v[6:7], v[6:7], v[10:11]
	v_pk_mul_f32 v[14:15], v[56:57], v[28:29] op_sel_hi:[1,0]
	v_cvt_pk_bf16_f32 v5, v6, v7
	global_store_dwordx2 v[2:3], v[4:5], off offset:16
	s_nop 1
	v_mov_b32_e32 v10, v172
	v_mov_b32_e32 v11, v173
	s_nop 0
	s_nop 1
	v_mov_b32_e32 v4, v220
	v_mov_b32_e32 v5, v221
	v_mov_b32_e32 v6, v222
	v_mov_b32_e32 v7, v223
	s_waitcnt vmcnt(1)
	v_lshlrev_b32_e32 v12, 16, v10
	v_and_b32_e32 v13, 0xffff0000, v10
	s_waitcnt vmcnt(0)
	v_pk_mul_f32 v[4:5], v[14:15], v[4:5]
	v_lshlrev_b32_e32 v10, 16, v11
	v_pk_mul_f32 v[4:5], v[4:5], v[12:13]
	v_pk_mul_f32 v[12:13], v[58:59], v[28:29] op_sel_hi:[1,0]
	v_and_b32_e32 v11, 0xffff0000, v11
	v_pk_mul_f32 v[6:7], v[12:13], v[6:7]
	v_cvt_pk_bf16_f32 v4, v4, v5
	v_pk_mul_f32 v[6:7], v[6:7], v[10:11]
	v_pk_mul_f32 v[12:13], v[60:61], v[28:29] op_sel_hi:[1,0]
	v_cvt_pk_bf16_f32 v5, v6, v7
	global_store_dwordx2 v[2:3], v[4:5], off offset:32
	s_nop 1
	v_mov_b32_e32 v10, v174
	v_mov_b32_e32 v11, v175
	s_nop 0
	s_nop 1
	v_mov_b32_e32 v4, v224
	v_mov_b32_e32 v5, v225
	v_mov_b32_e32 v6, v226
	v_mov_b32_e32 v7, v227
	v_pk_mul_f32 v[14:15], v[62:63], v[28:29] op_sel_hi:[1,0]
	s_waitcnt vmcnt(1)
	v_lshlrev_b32_e32 v32, 16, v10
	v_and_b32_e32 v33, 0xffff0000, v10
	v_lshlrev_b32_e32 v10, 16, v11
	v_and_b32_e32 v11, 0xffff0000, v11
	s_waitcnt vmcnt(0)
	v_pk_mul_f32 v[4:5], v[12:13], v[4:5]
	v_pk_mul_f32 v[6:7], v[14:15], v[6:7]
	v_pk_mul_f32 v[4:5], v[4:5], v[32:33]
	v_pk_mul_f32 v[6:7], v[6:7], v[10:11]
	v_cvt_pk_bf16_f32 v4, v4, v5
	v_cvt_pk_bf16_f32 v5, v6, v7
	global_store_dwordx2 v[2:3], v[4:5], off offset:48
	s_nop 1
	v_mov_b32_e32 v10, v176
	v_mov_b32_e32 v11, v177
	s_nop 0
	s_nop 1
	v_mov_b32_e32 v4, v228
	v_mov_b32_e32 v5, v229
	v_mov_b32_e32 v6, v230
	v_mov_b32_e32 v7, v231
	v_add_co_u32_e32 v12, vcc, s6, v2
	v_pk_mul_f32 v[14:15], v[18:19], v[28:29] op_sel_hi:[1,0]
	s_nop 0
	v_addc_co_u32_e32 v13, vcc, 0, v3, vcc
	v_pk_mul_f32 v[2:3], v[16:17], v[28:29] op_sel_hi:[1,0]
	s_waitcnt vmcnt(1)
	v_lshlrev_b32_e32 v16, 16, v10
	v_and_b32_e32 v17, 0xffff0000, v10
	v_lshlrev_b32_e32 v10, 16, v11
	v_and_b32_e32 v11, 0xffff0000, v11
	s_waitcnt vmcnt(0)
	v_pk_mul_f32 v[2:3], v[2:3], v[4:5]
	v_pk_mul_f32 v[4:5], v[14:15], v[6:7]
	v_pk_mul_f32 v[2:3], v[2:3], v[16:17]
	v_pk_mul_f32 v[4:5], v[4:5], v[10:11]
	v_cvt_pk_bf16_f32 v2, v2, v3
	v_cvt_pk_bf16_f32 v3, v4, v5
	global_store_dwordx2 v[12:13], v[2:3], off
	s_nop 1
	v_mov_b32_e32 v6, v178
	v_mov_b32_e32 v7, v179
	s_nop 0
	s_nop 1
	v_mov_b32_e32 v2, v232
	v_mov_b32_e32 v3, v233
	v_mov_b32_e32 v4, v234
	v_mov_b32_e32 v5, v235
	v_pk_mul_f32 v[10:11], v[20:21], v[28:29] op_sel_hi:[1,0]
	v_pk_mul_f32 v[14:15], v[22:23], v[28:29] op_sel_hi:[1,0]
	s_waitcnt vmcnt(1)
	v_lshlrev_b32_e32 v16, 16, v6
	v_and_b32_e32 v17, 0xffff0000, v6
	v_lshlrev_b32_e32 v6, 16, v7
	v_and_b32_e32 v7, 0xffff0000, v7
	s_waitcnt vmcnt(0)
	v_pk_mul_f32 v[2:3], v[10:11], v[2:3]
	v_pk_mul_f32 v[4:5], v[14:15], v[4:5]
	v_pk_mul_f32 v[2:3], v[2:3], v[16:17]
	v_pk_mul_f32 v[4:5], v[4:5], v[6:7]
	v_cvt_pk_bf16_f32 v2, v2, v3
	v_cvt_pk_bf16_f32 v3, v4, v5
	global_store_dwordx2 v[12:13], v[2:3], off offset:16
	s_nop 1
	v_mov_b32_e32 v6, v180
	v_mov_b32_e32 v7, v181
	s_nop 0
	s_nop 1
	v_mov_b32_e32 v2, v236
	v_mov_b32_e32 v3, v237
	v_mov_b32_e32 v4, v238
	v_mov_b32_e32 v5, v239
	v_pk_mul_f32 v[10:11], v[24:25], v[28:29] op_sel_hi:[1,0]
	v_pk_mul_f32 v[14:15], v[26:27], v[28:29] op_sel_hi:[1,0]
	s_waitcnt vmcnt(1)
	v_lshlrev_b32_e32 v16, 16, v6
	v_and_b32_e32 v17, 0xffff0000, v6
	v_lshlrev_b32_e32 v6, 16, v7
	v_and_b32_e32 v7, 0xffff0000, v7
	s_waitcnt vmcnt(0)
	v_pk_mul_f32 v[2:3], v[10:11], v[2:3]
	v_pk_mul_f32 v[4:5], v[14:15], v[4:5]
	v_pk_mul_f32 v[2:3], v[2:3], v[16:17]
	v_pk_mul_f32 v[4:5], v[4:5], v[6:7]
	v_cvt_pk_bf16_f32 v2, v2, v3
	v_cvt_pk_bf16_f32 v3, v4, v5
	global_store_dwordx2 v[12:13], v[2:3], off offset:32
	s_nop 1
	v_mov_b32_e32 v4, v182
	v_mov_b32_e32 v5, v183
	s_nop 0
	s_nop 1
	v_mov_b32_e32 v0, v240
	v_mov_b32_e32 v1, v241
	v_mov_b32_e32 v2, v242
	v_mov_b32_e32 v3, v243
	v_pk_mul_f32 v[6:7], v[8:9], v[28:29] op_sel_hi:[1,0]
	v_pk_mul_f32 v[8:9], v[30:31], v[28:29] op_sel_hi:[1,0]
	s_mov_b64 s[4:5], 0
	s_waitcnt vmcnt(1)
	v_lshlrev_b32_e32 v10, 16, v4
	v_and_b32_e32 v11, 0xffff0000, v4
	v_lshlrev_b32_e32 v4, 16, v5
	v_and_b32_e32 v5, 0xffff0000, v5
	s_waitcnt vmcnt(0)
	v_pk_mul_f32 v[0:1], v[6:7], v[0:1]
	v_pk_mul_f32 v[2:3], v[8:9], v[2:3]
	v_pk_mul_f32 v[0:1], v[0:1], v[10:11]
	v_pk_mul_f32 v[2:3], v[2:3], v[4:5]
	v_cvt_pk_bf16_f32 v0, v0, v1
	v_cvt_pk_bf16_f32 v1, v2, v3
	global_store_dwordx2 v[12:13], v[0:1], off offset:48
	s_branch .LBB0_71

; #define MFMA(a, b, c) __builtin_amdgcn_mfma_f32_32x32x16_bf16((a), (b), (c), 0, 0, 0)
; #define LOAD_VF() do { \
;             __builtin_amdgcn_sched_barrier(0); \
;             _Pragma("unroll") for (int s = 0; s < 4; ++s) \
;                 _Pragma("unroll") for (int dt = 0; dt < 2; ++dt) vf[2 * s + dt] = ldv_frag(sv, 32 * dt + r, 2 * s + h, xr); \
;             __builtin_amdgcn_sched_barrier(0); } while (0)
; template <int KIND>
; DI void attn_unit(const Params& p, int l, int b, int head, int qt, int qcol, int kcol, int vfeat, int gcol, int mixcol,
;                   int t1, int n1, int t2, int n2, char* smem) {
;     ...
;                 f32x16 S[2];
; #pragma unroll
;                 for (int t = 0; t < 2; ++t) S[t] = MFMA(kf[t], qf[0], cz);
; #pragma unroll
;                 for (int s = 1; s < 4; ++s)
; #pragma unroll
;                     for (int t = 0; t < 2; ++t) S[t] = MFMA(kf[2 * s + t], qf[s], S[t]);
;                 LOAD_VF();
;                 if (KIND == 2 && tile < 32) {
;                     const char* brow = smem + ATT_BIAS + (tile - nrow + 7) * 128;
; #pragma unroll
;                     for (int t = 0; t < 2; ++t)
; #pragma unroll
;                         for (int e = 0; e < 16; ++e) S[t][e] += *(const float*)(brow + bcol[t][e]);
;                 }
;                 softmax_tile(S, l0);
;                 pv_tile(S, O0, vf);
;             }
.Lk1_drain:
	s_mov_b32 s35, s34
	v_exp_f32_e32 v238, v56
	v_exp_f32_e32 v239, v57
	v_exp_f32_e32 v240, v58
	v_exp_f32_e32 v241, v59
	v_exp_f32_e32 v242, v60
	v_exp_f32_e32 v243, v61
	v_exp_f32_e32 v244, v62
	v_exp_f32_e32 v245, v63
	v_cvt_pk_bf16_f32 v176, v214, v215
	v_cvt_pk_bf16_f32 v177, v216, v217
	v_add_f32_e32 v199, v214, v216
	v_add_f32_e32 v192, v215, v217
	v_add_f32_e32 v199, v218, v199
	v_add_f32_e32 v192, v219, v192
	v_cvt_pk_bf16_f32 v178, v218, v219
	v_cvt_pk_bf16_f32 v179, v220, v221
	v_add_f32_e32 v199, v220, v199
	v_add_f32_e32 v192, v221, v192
	v_add_f32_e32 v199, v222, v199
	v_add_f32_e32 v192, v223, v192
	v_cvt_pk_bf16_f32 v180, v222, v223
	v_cvt_pk_bf16_f32 v181, v224, v225
	v_add_f32_e32 v199, v224, v199
	v_add_f32_e32 v192, v225, v192
	v_add_f32_e32 v199, v226, v199
	v_add_f32_e32 v192, v227, v192
	v_cvt_pk_bf16_f32 v182, v226, v227
	v_cvt_pk_bf16_f32 v183, v228, v229
	v_add_f32_e32 v199, v228, v199
	v_add_f32_e32 v192, v229, v192
	v_add_f32_e32 v199, v230, v199
	v_add_f32_e32 v192, v231, v192
	v_cvt_pk_bf16_f32 v184, v230, v231
	v_cvt_pk_bf16_f32 v185, v232, v233
	v_add_f32_e32 v199, v232, v199
	v_add_f32_e32 v192, v233, v192
	v_add_f32_e32 v199, v234, v199
	v_add_f32_e32 v192, v235, v192
	v_cvt_pk_bf16_f32 v186, v234, v235
	v_cvt_pk_bf16_f32 v187, v236, v237
	v_add_f32_e32 v199, v236, v199
	v_add_f32_e32 v192, v237, v192
	v_add_f32_e32 v199, v238, v199
	v_add_f32_e32 v192, v239, v192
	v_cvt_pk_bf16_f32 v188, v238, v239
	v_cvt_pk_bf16_f32 v189, v240, v241
	v_add_f32_e32 v199, v240, v199
	v_add_f32_e32 v192, v241, v192
	v_add_f32_e32 v199, v242, v199
	v_add_f32_e32 v192, v243, v192
	v_cvt_pk_bf16_f32 v190, v242, v243
	v_cvt_pk_bf16_f32 v191, v244, v245
	v_add_f32_e32 v199, v244, v199
	v_add_f32_e32 v192, v245, v192
	v_add_f32_e32 v199, v199, v192
	v_add_f32_e32 v104, v104, v199
	s_waitcnt lgkmcnt(0)
	v_mfma_f32_32x32x16_bf16 v[32:47], v[110:113], v[176:179], v[32:47]
	v_mfma_f32_32x32x16_bf16 v[0:15], v[114:117], v[176:179], v[0:15]
	v_mfma_f32_32x32x16_bf16 v[32:47], v[118:121], v[180:183], v[32:47]
	v_mfma_f32_32x32x16_bf16 v[0:15], v[122:125], v[180:183], v[0:15]
	v_mfma_f32_32x32x16_bf16 v[32:47], v[126:129], v[184:187], v[32:47]
	v_mfma_f32_32x32x16_bf16 v[0:15], v[130:133], v[184:187], v[0:15]
	v_mfma_f32_32x32x16_bf16 v[32:47], v[134:137], v[188:191], v[32:47]
	v_mfma_f32_32x32x16_bf16 v[0:15], v[138:141], v[188:191], v[0:15]
	s_lshl_b32 s4, s35, 14
	s_add_i32 s5, s4, 32
	v_add_u32_e32 v52, s5, v105
	v_add_u32_e32 v100, v52, v107
	v_add_u32_e32 v132, v52, v106
	v_add_u32_e32 v133, v52, v103
	v_add_u32_e32 v134, v52, v101
	s_waitcnt vmcnt(4)
	s_barrier
	ds_read_b128 v[48:51], v100
	ds_read_b128 v[96:99], v100 offset:4096
	ds_read_b128 v[108:111], v132
	ds_read_b128 v[112:115], v132 offset:4096
	ds_read_b128 v[116:119], v133
	ds_read_b128 v[120:123], v133 offset:4096
	ds_read_b128 v[124:127], v134
	ds_read_b128 v[128:131], v134 offset:4096
	s_waitcnt lgkmcnt(0)
	v_mfma_f32_32x32x16_bf16 v[64:79], v[48:51], v[92:95], v[16:31]
	v_mfma_f32_32x32x16_bf16 v[48:63], v[96:99], v[92:95], v[16:31]
	v_mfma_f32_32x32x16_bf16 v[64:79], v[108:111], v[88:91], v[64:79]
	v_mfma_f32_32x32x16_bf16 v[48:63], v[112:115], v[88:91], v[48:63]
	v_mfma_f32_32x32x16_bf16 v[64:79], v[116:119], v[84:87], v[64:79]
	v_mfma_f32_32x32x16_bf16 v[48:63], v[120:123], v[84:87], v[48:63]
	v_mfma_f32_32x32x16_bf16 v[64:79], v[124:127], v[80:83], v[64:79]
	v_mfma_f32_32x32x16_bf16 v[48:63], v[128:131], v[80:83], v[48:63]
	ds_read_b128 v[96:99], v100 offset:8192
	ds_read_b128 v[108:111], v100 offset:12288
	ds_read_b128 v[112:115], v132 offset:8192
	ds_read_b128 v[116:119], v132 offset:12288
	ds_read_b128 v[120:123], v133 offset:8192
	ds_read_b128 v[124:127], v133 offset:12288
	ds_read_b128 v[128:131], v134 offset:8192
	ds_read_b128 v[132:135], v134 offset:12288
	s_nop 2
	v_exp_f32_e32 v64, v64
	v_exp_f32_e32 v65, v65
	v_exp_f32_e32 v66, v66
	v_exp_f32_e32 v67, v67
	v_exp_f32_e32 v68, v68
	v_exp_f32_e32 v69, v69
	v_exp_f32_e32 v70, v70
	v_exp_f32_e32 v71, v71
	v_add_f32_e64 v136, v64, 0
	v_add_f32_e64 v137, v65, 0
	v_exp_f32_e32 v72, v72
	v_add_f32_e64 v136, v66, v136
	v_add_f32_e64 v137, v67, v137
	v_exp_f32_e32 v73, v73
	v_cvt_pk_bf16_f32 v64, v64, v65
	v_cvt_pk_bf16_f32 v65, v66, v67
	v_cvt_pk_bf16_f32 v66, v68, v69
	v_cvt_pk_bf16_f32 v67, v70, v71
	v_exp_f32_e32 v74, v74
	v_exp_f32_e32 v75, v75
	s_waitcnt lgkmcnt(0)
	v_mfma_f32_32x32x16_bf16 v[32:47], v[96:99], v[64:67], v[32:47]
	v_add_f32_e64 v136, v68, v136
	v_add_f32_e64 v137, v69, v137
	v_exp_f32_e32 v68, v76
	v_exp_f32_e32 v69, v77
	v_add_f32_e64 v136, v70, v136
	v_add_f32_e64 v137, v71, v137
	v_exp_f32_e32 v70, v78
	v_exp_f32_e32 v71, v79
	v_add_f32_e64 v136, v72, v136
	v_add_f32_e64 v137, v73, v137
	v_mfma_f32_32x32x16_bf16 v[0:15], v[108:111], v[64:67], v[0:15]
	v_exp_f32_e32 v48, v48
	v_exp_f32_e32 v49, v49
	v_add_f32_e64 v136, v74, v136
	v_add_f32_e64 v137, v75, v137
	v_exp_f32_e32 v50, v50
	v_add_f32_e64 v76, v68, v136
	v_add_f32_e64 v77, v69, v137
	v_cvt_pk_bf16_f32 v66, v68, v69
	v_add_f32_e64 v64, v70, v76
	v_add_f32_e64 v65, v71, v77
	v_cvt_pk_bf16_f32 v67, v70, v71
	v_add_f32_e64 v76, v48, v64
	v_add_f32_e64 v77, v49, v65
	v_cvt_pk_bf16_f32 v64, v72, v73
	v_cvt_pk_bf16_f32 v65, v74, v75
	v_exp_f32_e32 v51, v51
	v_exp_f32_e32 v52, v52
	v_mfma_f32_32x32x16_bf16 v[32:47], v[112:115], v[64:67], v[32:47]
	v_exp_f32_e32 v53, v53
	v_exp_f32_e32 v54, v54
	v_exp_f32_e32 v55, v55
	v_add_f32_e64 v68, v50, v76
	v_add_f32_e64 v69, v51, v77
	v_exp_f32_e32 v56, v56
	v_add_f32_e64 v68, v52, v68
	v_add_f32_e64 v69, v53, v69
	v_exp_f32_e32 v57, v57
	v_mfma_f32_32x32x16_bf16 v[0:15], v[116:119], v[64:67], v[0:15]
	v_add_f32_e64 v64, v54, v68
	v_add_f32_e64 v65, v55, v69
	v_cvt_pk_bf16_f32 v48, v48, v49
	v_cvt_pk_bf16_f32 v49, v50, v51
	v_cvt_pk_bf16_f32 v51, v54, v55
	v_exp_f32_e32 v54, v58
	v_exp_f32_e32 v55, v59
	s_addk_i32 s4, 0x4000
	s_cmp_lg_u32 s35, 2
	v_cvt_pk_bf16_f32 v50, v52, v53
	s_cselect_b32 s4, s4, 0
	v_add_f32_e64 v52, v56, v64
	v_add_f32_e64 v53, v57, v65
	v_mfma_f32_32x32x16_bf16 v[32:47], v[120:123], v[48:51], v[32:47]
	s_add_i32 s4, s4, 32
	v_exp_f32_e32 v58, v60
	v_exp_f32_e32 v59, v61
	v_exp_f32_e32 v60, v62
	v_exp_f32_e32 v61, v63
	s_waitcnt vmcnt(0)
	s_barrier
; #define MFMA(a, b, c) __builtin_amdgcn_mfma_f32_32x32x16_bf16((a), (b), (c), 0, 0, 0)
; DI unsigned pk2(float a, float b) { f2_t v = {a, b}; bf2_t r = __builtin_convertvector(v, bf2_t); return __builtin_bit_cast(unsigned, r); }
; DI float bf2f(bf16_t v) { return __uint_as_float(((unsigned)v) << 16); }
; DI int otid() { int t = threadIdx.x; asm volatile("" : "+v"(t)); return t; }
; template <int KIND>
; DI void attn_unit(const Params& p, int l, int b, int head, int qt, int qcol, int kcol, int vfeat, int gcol, int mixcol,
;                   int t1, int n1, int t2, int n2, char* smem) {
;     ...
;                 f32x16 S[2];
; #pragma unroll
;                 for (int t = 0; t < 2; ++t) S[t] = MFMA(kf[t], qf[0], cz);
; #pragma unroll
;                 for (int s = 1; s < 4; ++s)
; #pragma unroll
;                     for (int t = 0; t < 2; ++t) S[t] = MFMA(kf[2 * s + t], qf[s], S[t]);
;                 LOAD_VF();
;                 if (KIND == 2 && tile < 32) {
;                     const char* brow = smem + ATT_BIAS + (tile - nrow + 7) * 128;
; #pragma unroll
;                     for (int t = 0; t < 2; ++t)
; #pragma unroll
;                         for (int e = 0; e < 16; ++e) S[t][e] += *(const float*)(brow + bcol[t][e]);
;                 }
;                 softmax_tile(S, l0);
;                 pv_tile(S, O0, vf);
;             }
;     ...
;         }
;     }
;     l0 = xsum32(l0);
;     const float inv0 = 1.f / l0;
;     const int tid_e = otid();
;     const size_t qrow_e = (size_t)b * TPB + qt * 128 + 32 * (tid_e >> 6) + (tid_e & 31);
;     bf16_t* orow = p.hmix + ((size_t)(mixcol >> 5) * NTOK + qrow_e) * 32;
;     const bf16_t* grow = p.qkv + ((size_t)(gcol >> 6) * NTOK + qrow_e) * 64;
;     ...
;         for (int t = 0; t < 2; ++t)
; #pragma unroll
;             for (int q = 0; q < 4; ++q) {
;                 const int f = 32 * t + 8 * q + 4 * h;
;                 const uint2 gg = *(const uint2*)(grow + f);
;                 const float g0 = bf2f((bf16_t)(gg.x & 0xffff)), g1 = bf2f((bf16_t)(gg.x >> 16)), g2 = bf2f((bf16_t)(gg.y & 0xffff)), g3 = bf2f((bf16_t)(gg.y >> 16));
;                 uint2 o;
;                 o.x = pk2(O0[t][4 * q + 0] * inv0 * g0, O0[t][4 * q + 1] * inv0 * g1);
;                 o.y = pk2(O0[t][4 * q + 2] * inv0 * g2, O0[t][4 * q + 3] * inv0 * g3);
;                 *(uint2*)(orow + (size_t)t * NTOK * 32 + 8 * q + 4 * h) = o;
;             }
	v_mfma_f32_32x32x16_bf16 v[0:15], v[124:127], v[48:51], v[0:15]
	v_add_f32_e64 v48, v54, v52
	v_add_f32_e64 v49, v55, v53
	v_add_u32_e32 v52, s4, v105
	v_add_u32_e32 v105, v52, v107
	v_add_u32_e32 v118, v52, v106
	v_add_u32_e32 v103, v52, v103
	v_add_u32_e32 v119, v52, v101
	ds_read_b128 v[64:67], v105
	ds_read_b128 v[68:71], v105 offset:4096
	ds_read_b128 v[72:75], v118
	ds_read_b128 v[76:79], v118 offset:4096
	ds_read_b128 v[106:109], v103
	ds_read_b128 v[110:113], v103 offset:4096
	ds_read_b128 v[98:101], v119
	ds_read_b128 v[114:117], v119 offset:4096
	v_add_f32_e64 v48, v58, v48
	v_add_f32_e64 v49, v59, v49
	v_cvt_pk_bf16_f32 v50, v58, v59
	v_add_f32_e64 v96, v60, v48
	v_add_f32_e64 v97, v61, v49
	v_cvt_pk_bf16_f32 v48, v56, v57
	v_cvt_pk_bf16_f32 v49, v54, v55
	v_cvt_pk_bf16_f32 v51, v60, v61
	s_nop 1
	v_mfma_f32_32x32x16_bf16 v[32:47], v[128:131], v[48:51], v[32:47]
	v_mfma_f32_32x32x16_bf16 v[0:15], v[132:135], v[48:51], v[0:15]
	s_waitcnt lgkmcnt(0)
	v_mfma_f32_32x32x16_bf16 v[48:63], v[64:67], v[92:95], v[16:31]
	v_mfma_f32_32x32x16_bf16 v[16:31], v[68:71], v[92:95], v[16:31]
	v_mfma_f32_32x32x16_bf16 v[48:63], v[72:75], v[88:91], v[48:63]
	v_mfma_f32_32x32x16_bf16 v[16:31], v[76:79], v[88:91], v[16:31]
	v_mfma_f32_32x32x16_bf16 v[48:63], v[106:109], v[84:87], v[48:63]
	v_mfma_f32_32x32x16_bf16 v[16:31], v[110:113], v[84:87], v[16:31]
	v_mfma_f32_32x32x16_bf16 v[48:63], v[98:101], v[80:83], v[48:63]
	v_mfma_f32_32x32x16_bf16 v[16:31], v[114:117], v[80:83], v[16:31]
	ds_read_b128 v[92:95], v105 offset:8192
	ds_read_b128 v[76:79], v105 offset:12288
	ds_read_b128 v[88:91], v118 offset:8192
	ds_read_b128 v[72:75], v118 offset:12288
	ds_read_b128 v[84:87], v103 offset:8192
	ds_read_b128 v[68:71], v103 offset:12288
	ds_read_b128 v[80:83], v119 offset:8192
	ds_read_b128 v[64:67], v119 offset:12288
	s_nop 2
	v_exp_f32_e32 v98, v48
	v_exp_f32_e32 v99, v49
	v_exp_f32_e32 v50, v50
	v_exp_f32_e32 v51, v51
	v_exp_f32_e32 v52, v52
	v_exp_f32_e32 v53, v53
	v_exp_f32_e32 v54, v54
	v_exp_f32_e32 v55, v55
	v_add_f32_e64 v48, v98, 0
	v_add_f32_e64 v49, v99, 0
	v_exp_f32_e32 v56, v56
	v_exp_f32_e32 v57, v57
	v_add_f32_e64 v48, v50, v48
	v_add_f32_e64 v49, v51, v49
	v_mov_b32_e32 v103, v200
	v_add_f32_e64 v48, v52, v48
	v_add_f32_e64 v49, v53, v49
	s_add_u32 s4, s29, s6
	v_add_f32_e64 v48, v54, v48
	v_add_f32_e64 v49, v55, v49
	s_addc_u32 s5, s7, 0
	v_add_f32_e64 v100, v56, v48
	v_add_f32_e64 v101, v57, v49
	v_ashrrev_i32_e32 v48, 1, v103
	v_and_b32_e32 v48, 0xffffffe0, v48
	v_ashrrev_i32_e32 v49, 31, v48
	v_and_or_b32 v106, v103, 31, s4
	v_mov_b32_e32 v107, s5
	s_lshr_b32 s4, s9, 6
	v_lshl_add_u64 v[106:107], v[106:107], 0, v[48:49]
	s_mulk_i32 s4, 0x4800
	s_mov_b32 s5, s75
	v_lshl_add_u64 v[48:49], v[106:107], 0, s[4:5]
	v_lshlrev_b64 v[48:49], 7, v[48:49]
	v_lshl_add_u64 v[48:49], s[40:41], 0, v[48:49]
	v_lshlrev_b32_e32 v192, 3, v102
	v_lshl_add_u64 v[48:49], v[48:49], 0, v[192:193]
	global_load_dwordx2 v[102:103], v[48:49], off
	global_load_dwordx2 v[214:215], v[48:49], off offset:16
	global_load_dwordx2 v[216:217], v[48:49], off offset:32
	global_load_dwordx2 v[218:219], v[48:49], off offset:48
	global_load_dwordx2 v[220:221], v[48:49], off offset:64
	global_load_dwordx2 v[222:223], v[48:49], off offset:80
	global_load_dwordx2 v[224:225], v[48:49], off offset:96
	global_load_dwordx2 v[226:227], v[48:49], off offset:112
	v_exp_f32_e32 v58, v58
	v_exp_f32_e32 v59, v59
	v_exp_f32_e32 v60, v60
	v_exp_f32_e32 v61, v61
	v_exp_f32_e32 v62, v62
	v_exp_f32_e32 v63, v63
	v_exp_f32_e32 v114, v28
	v_exp_f32_e32 v115, v29
	v_exp_f32_e32 v116, v30
	v_exp_f32_e32 v117, v31
	v_cvt_pk_bf16_f32 v28, v98, v99
	v_cvt_pk_bf16_f32 v29, v50, v51
	v_cvt_pk_bf16_f32 v30, v52, v53
	v_cvt_pk_bf16_f32 v31, v54, v55
	v_exp_f32_e32 v16, v16
	v_exp_f32_e32 v17, v17
	s_waitcnt lgkmcnt(0)
	v_mfma_f32_32x32x16_bf16 v[32:47], v[92:95], v[28:31], v[32:47]
	v_add_f32_e64 v100, v58, v100
	v_add_f32_e64 v101, v59, v101
	v_exp_f32_e32 v18, v18
	v_exp_f32_e32 v19, v19
	v_add_f32_e64 v100, v60, v100
	v_add_f32_e64 v101, v61, v101
	v_exp_f32_e32 v108, v20
	v_exp_f32_e32 v109, v21
	v_add_f32_e64 v100, v62, v100
	v_add_f32_e64 v101, v63, v101
	v_exp_f32_e32 v110, v22
	v_exp_f32_e32 v111, v23
	v_add_f32_e64 v20, v16, v100
	v_add_f32_e64 v21, v17, v101
	v_exp_f32_e32 v100, v24
	v_exp_f32_e32 v101, v25
	v_add_f32_e64 v20, v18, v20
	v_add_f32_e64 v21, v19, v21
	v_exp_f32_e32 v112, v26
	v_exp_f32_e32 v113, v27
	v_add_f32_e64 v20, v108, v20
	v_add_f32_e64 v21, v109, v21
	v_cvt_pk_bf16_f32 v24, v56, v57
	v_add_f32_e64 v20, v110, v20
	v_add_f32_e64 v21, v111, v21
	v_cvt_pk_bf16_f32 v25, v58, v59
	v_cvt_pk_bf16_f32 v26, v60, v61
	v_cvt_pk_bf16_f32 v27, v62, v63
	v_add_f32_e64 v20, v100, v20
	v_add_f32_e64 v21, v101, v21
	v_mov_b32_e32 v22, v96
	v_mfma_f32_32x32x16_bf16 v[32:47], v[88:91], v[24:27], v[32:47]
	v_add_f32_e64 v20, v112, v20
	v_add_f32_e64 v21, v113, v21
	s_lshr_b32 s6, s8, 5
	v_add_f32_e64 v20, v114, v20
	v_add_f32_e64 v21, v115, v21
	s_mulk_i32 s6, 0x4800
	v_add_f32_e64 v20, v116, v20
	v_add_f32_e64 v21, v117, v21
	s_ashr_i32 s7, s6, 31
	v_mov_b32_e32 v23, v20
	v_mov_b32_e32 v20, v97
	v_add_f32_e64 v20, v22, v20
	v_add_f32_e64 v21, v23, v21
	v_cvt_pk_bf16_f32 v22, v108, v109
	v_add_f32_e32 v20, v104, v20
	v_add_f32_e32 v50, v20, v21
	v_cvt_pk_bf16_f32 v20, v16, v17
	v_cvt_pk_bf16_f32 v21, v18, v19
	v_cvt_pk_bf16_f32 v23, v110, v111
	v_mov_b32_e32 v18, v50
	s_nop 1
	v_permlane32_swap_b32_e32 v50, v18
	v_mfma_f32_32x32x16_bf16 v[32:47], v[84:87], v[20:23], v[32:47]
	v_add_f32_e32 v50, v50, v18
	v_div_scale_f32 v51, s[4:5], v50, v50, 1.0
	v_rcp_f32_e32 v52, v51
	v_cvt_pk_bf16_f32 v16, v100, v101
	v_cvt_pk_bf16_f32 v17, v112, v113
	v_cvt_pk_bf16_f32 v18, v114, v115
	v_cvt_pk_bf16_f32 v19, v116, v117
	v_fma_f32 v53, -v51, v52, 1.0
	v_fmac_f32_e32 v52, v53, v52
	v_mfma_f32_32x32x16_bf16 v[32:47], v[80:83], v[16:19], v[32:47]
	v_div_scale_f32 v53, vcc, 1.0, v50, 1.0
	v_mul_f32_e32 v54, v53, v52
	v_fma_f32 v55, -v51, v54, v53
	v_fmac_f32_e32 v54, v55, v52
	s_load_dwordx2 s[4:5], s[0:1], 0xb8
	v_fma_f32 v51, -v51, v54, v53
	v_div_fmas_f32 v51, v51, v52, v54
	v_div_fixup_f32 v50, v51, v50, 1.0
	v_lshl_add_u64 v[52:53], v[106:107], 0, s[6:7]
	v_lshlrev_b64 v[52:53], 6, v[52:53]
	s_waitcnt vmcnt(0)
; DI unsigned pk2(float a, float b) { f2_t v = {a, b}; bf2_t r = __builtin_convertvector(v, bf2_t); return __builtin_bit_cast(unsigned, r); }
; DI float bf2f(bf16_t v) { return __uint_as_float(((unsigned)v) << 16); }
; template <int KIND>
; DI void attn_unit(const Params& p, int l, int b, int head, int qt, int qcol, int kcol, int vfeat, int gcol, int mixcol,
;                   int t1, int n1, int t2, int n2, char* smem) {
;     ...
; #pragma unroll
;         for (int t = 0; t < 2; ++t)
; #pragma unroll
;             for (int q = 0; q < 4; ++q) {
;                 const int f = 32 * t + 8 * q + 4 * h;
;                 const uint2 gg = *(const uint2*)(grow + f);
;                 const float g0 = bf2f((bf16_t)(gg.x & 0xffff)), g1 = bf2f((bf16_t)(gg.x >> 16)), g2 = bf2f((bf16_t)(gg.y & 0xffff)), g3 = bf2f((bf16_t)(gg.y >> 16));
;                 uint2 o;
;                 o.x = pk2(O0[t][4 * q + 0] * inv0 * g0, O0[t][4 * q + 1] * inv0 * g1);
;                 o.y = pk2(O0[t][4 * q + 2] * inv0 * g2, O0[t][4 * q + 3] * inv0 * g3);
;                 *(uint2*)(orow + (size_t)t * NTOK * 32 + 8 * q + 4 * h) = o;
;             }
	v_lshlrev_b32_e32 v54, 16, v102
	v_and_b32_e32 v55, 0xffff0000, v102
	v_lshlrev_b32_e32 v56, 16, v103
	v_and_b32_e32 v57, 0xffff0000, v103
	v_pk_mul_f32 v[32:33], v[32:33], v[50:51] op_sel_hi:[1,0]
	v_pk_mul_f32 v[34:35], v[34:35], v[50:51] op_sel_hi:[1,0]
	s_waitcnt lgkmcnt(0)
	v_lshl_add_u64 v[52:53], s[4:5], 0, v[52:53]
	v_pk_mul_f32 v[32:33], v[32:33], v[54:55]
	v_pk_mul_f32 v[34:35], v[34:35], v[56:57]
	v_lshl_add_u64 v[52:53], v[52:53], 0, v[192:193]
	v_cvt_pk_bf16_f32 v32, v32, v33
	v_cvt_pk_bf16_f32 v33, v34, v35
	global_store_dwordx2 v[52:53], v[32:33], off
	s_nop 1
	v_mov_b32_e32 v32, v214
	v_mov_b32_e32 v33, v215
	v_mfma_f32_32x32x16_bf16 v[0:15], v[76:79], v[28:31], v[0:15]
	v_mul_f32_e64 v28, v36, v50
	v_mul_f32_e64 v29, v37, v50
	v_mul_f32_e64 v30, v38, v50
	v_mul_f32_e64 v31, v39, v50
	s_mov_b32 s4, 0x120000
	s_waitcnt vmcnt(0)
	v_lshlrev_b32_e32 v34, 16, v32
	v_and_b32_e32 v35, 0xffff0000, v32
	v_lshlrev_b32_e32 v32, 16, v33
	v_and_b32_e32 v33, 0xffff0000, v33
	v_pk_mul_f32 v[28:29], v[28:29], v[34:35]
	v_pk_mul_f32 v[30:31], v[30:31], v[32:33]
	v_cvt_pk_bf16_f32 v28, v28, v29
	v_cvt_pk_bf16_f32 v29, v30, v31
	global_store_dwordx2 v[52:53], v[28:29], off offset:16
	s_nop 1
	v_mov_b32_e32 v28, v216
	v_mov_b32_e32 v29, v217
	v_mfma_f32_32x32x16_bf16 v[0:15], v[72:75], v[24:27], v[0:15]
	v_mul_f32_e64 v24, v40, v50
	v_mul_f32_e64 v25, v41, v50
	v_mul_f32_e64 v26, v42, v50
	v_mul_f32_e64 v27, v43, v50
	s_waitcnt vmcnt(0)
	v_lshlrev_b32_e32 v30, 16, v28
	v_and_b32_e32 v31, 0xffff0000, v28
	v_lshlrev_b32_e32 v28, 16, v29
	v_and_b32_e32 v29, 0xffff0000, v29
	v_pk_mul_f32 v[24:25], v[24:25], v[30:31]
	v_pk_mul_f32 v[26:27], v[26:27], v[28:29]
	v_cvt_pk_bf16_f32 v24, v24, v25
	v_cvt_pk_bf16_f32 v25, v26, v27
	global_store_dwordx2 v[52:53], v[24:25], off offset:32
	s_nop 1
	v_mov_b32_e32 v24, v218
	v_mov_b32_e32 v25, v219
	v_mfma_f32_32x32x16_bf16 v[0:15], v[68:71], v[20:23], v[0:15]
	v_mul_f32_e64 v20, v44, v50
	v_mul_f32_e64 v21, v45, v50
	v_mul_f32_e64 v22, v46, v50
	v_mul_f32_e64 v23, v47, v50
	s_waitcnt vmcnt(0)
	v_lshlrev_b32_e32 v26, 16, v24
	v_and_b32_e32 v27, 0xffff0000, v24
	v_lshlrev_b32_e32 v24, 16, v25
	v_and_b32_e32 v25, 0xffff0000, v25
	v_pk_mul_f32 v[20:21], v[20:21], v[26:27]
	v_pk_mul_f32 v[22:23], v[22:23], v[24:25]
	v_cvt_pk_bf16_f32 v20, v20, v21
	v_cvt_pk_bf16_f32 v21, v22, v23
	global_store_dwordx2 v[52:53], v[20:21], off offset:48
	s_nop 1
	v_mov_b32_e32 v20, v220
	v_mov_b32_e32 v21, v221
	v_mfma_f32_32x32x16_bf16 v[0:15], v[64:67], v[16:19], v[0:15]
	v_add_co_u32_e32 v22, vcc, s4, v52
	s_mov_b64 s[4:5], 0
	s_nop 0
	v_addc_co_u32_e32 v23, vcc, 0, v53, vcc
	s_waitcnt vmcnt(0)
	v_lshlrev_b32_e32 v16, 16, v20
	s_nop 5
	v_pk_mul_f32 v[0:1], v[0:1], v[50:51] op_sel_hi:[1,0]
	v_pk_mul_f32 v[2:3], v[2:3], v[50:51] op_sel_hi:[1,0]
	v_and_b32_e32 v17, 0xffff0000, v20
	v_lshlrev_b32_e32 v18, 16, v21
	v_and_b32_e32 v19, 0xffff0000, v21
	v_pk_mul_f32 v[0:1], v[0:1], v[16:17]
	v_pk_mul_f32 v[2:3], v[2:3], v[18:19]
	v_cvt_pk_bf16_f32 v0, v0, v1
	v_cvt_pk_bf16_f32 v1, v2, v3
	global_store_dwordx2 v[22:23], v[0:1], off
	s_nop 1
	v_mov_b32_e32 v0, v222
	v_mov_b32_e32 v1, v223
	v_pk_mul_f32 v[2:3], v[4:5], v[50:51] op_sel_hi:[1,0]
	v_pk_mul_f32 v[4:5], v[6:7], v[50:51] op_sel_hi:[1,0]
	s_waitcnt vmcnt(0)
	v_lshlrev_b32_e32 v6, 16, v0
	v_and_b32_e32 v7, 0xffff0000, v0
	v_lshlrev_b32_e32 v0, 16, v1
	v_and_b32_e32 v1, 0xffff0000, v1
	v_pk_mul_f32 v[2:3], v[2:3], v[6:7]
	v_pk_mul_f32 v[0:1], v[4:5], v[0:1]
	v_cvt_pk_bf16_f32 v2, v2, v3
	v_cvt_pk_bf16_f32 v3, v0, v1
	global_store_dwordx2 v[22:23], v[2:3], off offset:16
	s_nop 1
	v_mov_b32_e32 v0, v224
	v_mov_b32_e32 v1, v225
	v_pk_mul_f32 v[2:3], v[8:9], v[50:51] op_sel_hi:[1,0]
	v_pk_mul_f32 v[4:5], v[10:11], v[50:51] op_sel_hi:[1,0]
	s_waitcnt vmcnt(0)
	v_lshlrev_b32_e32 v6, 16, v0
	v_and_b32_e32 v7, 0xffff0000, v0
	v_lshlrev_b32_e32 v0, 16, v1
	v_and_b32_e32 v1, 0xffff0000, v1
	v_pk_mul_f32 v[2:3], v[2:3], v[6:7]
	v_pk_mul_f32 v[0:1], v[4:5], v[0:1]
	v_cvt_pk_bf16_f32 v2, v2, v3
	v_cvt_pk_bf16_f32 v3, v0, v1
	global_store_dwordx2 v[22:23], v[2:3], off offset:32
	s_nop 1
	v_mov_b32_e32 v0, v226
	v_mov_b32_e32 v1, v227
	v_pk_mul_f32 v[2:3], v[12:13], v[50:51] op_sel_hi:[1,0]
	v_pk_mul_f32 v[4:5], v[14:15], v[50:51] op_sel_hi:[1,0]
	s_waitcnt vmcnt(0)
	v_lshlrev_b32_e32 v6, 16, v0
	v_and_b32_e32 v7, 0xffff0000, v0
	v_lshlrev_b32_e32 v0, 16, v1
	v_and_b32_e32 v1, 0xffff0000, v1
	v_pk_mul_f32 v[2:3], v[2:3], v[6:7]
	v_pk_mul_f32 v[0:1], v[4:5], v[0:1]
	v_cvt_pk_bf16_f32 v2, v2, v3
	v_cvt_pk_bf16_f32 v3, v0, v1
	global_store_dwordx2 v[22:23], v[2:3], off offset:48
	s_branch .LBB0_85

; DI unsigned pk2(float a, float b) { f2_t v = {a, b}; bf2_t r = __builtin_convertvector(v, bf2_t); return __builtin_bit_cast(unsigned, r); }
; DI float bf2f(bf16_t v) { return __uint_as_float(((unsigned)v) << 16); }
; DI int otid() { int t = threadIdx.x; asm volatile("" : "+v"(t)); return t; }
; DI float xsum32(float x) { const unsigned u = __float_as_uint(x); const auto r2 = __builtin_amdgcn_permlane32_swap(u, u, false, false); return __uint_as_float(r2[0]) + __uint_as_float(r2[1]); }
; template <int KIND>
; DI void attn_unit(const Params& p, int l, int b, int head, int qt, int qcol, int kcol, int vfeat, int gcol, int mixcol,
;                   int t1, int n1, int t2, int n2, char* smem) {
;     ...
;     l0 = xsum32(l0);
;     const float inv0 = 1.f / l0;
;     const int tid_e = otid();
;     const size_t qrow_e = (size_t)b * TPB + qt * 128 + 32 * (tid_e >> 6) + (tid_e & 31);
;     bf16_t* orow = p.hmix + ((size_t)(mixcol >> 5) * NTOK + qrow_e) * 32;
;     const bf16_t* grow = p.qkv + ((size_t)(gcol >> 6) * NTOK + qrow_e) * 64;
;     ...
; #pragma unroll
;         for (int t = 0; t < 2; ++t)
; #pragma unroll
;             for (int q = 0; q < 4; ++q) {
;                 const int f = 32 * t + 8 * q + 4 * h;
;                 const uint2 gg = *(const uint2*)(grow + f);
;                 const float g0 = bf2f((bf16_t)(gg.x & 0xffff)), g1 = bf2f((bf16_t)(gg.x >> 16)), g2 = bf2f((bf16_t)(gg.y & 0xffff)), g3 = bf2f((bf16_t)(gg.y >> 16));
;                 uint2 o;
;                 o.x = pk2(O0[t][4 * q + 0] * inv0 * g0, O0[t][4 * q + 1] * inv0 * g1);
;                 o.y = pk2(O0[t][4 * q + 2] * inv0 * g2, O0[t][4 * q + 3] * inv0 * g3);
;                 *(uint2*)(orow + (size_t)t * NTOK * 32 + 8 * q + 4 * h) = o;
;             }
.LBB0_107:
	s_add_i32 s4, s35, 0xc80
	s_addk_i32 s35, 0x280
	v_mov_b32_e32 v34, v200
	s_add_u32 s5, s34, s28
	v_ashrrev_i32_e32 v32, 1, v34
	s_addc_u32 s6, s29, 0
	v_and_b32_e32 v32, 0xffffffe0, v32
	v_ashrrev_i32_e32 v33, 31, v32
	v_and_or_b32 v34, v34, 31, s5
	v_mov_b32_e32 v35, s6
	s_lshr_b32 s4, s4, 6
	v_lshl_add_u64 v[32:33], v[34:35], 0, v[32:33]
	s_mulk_i32 s4, 0x4800
	s_mov_b32 s5, s75
	v_lshl_add_u64 v[34:35], v[32:33], 0, s[4:5]
	v_lshlrev_b64 v[34:35], 7, v[34:35]
	v_lshl_add_u64 v[34:35], s[44:45], 0, v[34:35]
	v_lshlrev_b32_e32 v192, 1, v164
	v_lshl_add_u64 v[34:35], v[34:35], 0, v[192:193]
	global_load_dwordx2 v[36:37], v[34:35], off
	global_load_dwordx2 v[48:49], v[34:35], off offset:16
	global_load_dwordx2 v[50:51], v[34:35], off offset:32
	global_load_dwordx2 v[52:53], v[34:35], off offset:48
	global_load_dwordx2 v[54:55], v[34:35], off offset:64
	global_load_dwordx2 v[56:57], v[34:35], off offset:80
	global_load_dwordx2 v[58:59], v[34:35], off offset:96
	global_load_dwordx2 v[60:61], v[34:35], off offset:112
	v_mov_b32_e32 v38, v179
	s_nop 1
	v_permlane32_swap_b32_e32 v179, v38
	v_add_f32_e32 v38, v179, v38
	v_div_scale_f32 v39, s[8:9], v38, v38, 1.0
	v_rcp_f32_e32 v41, v39
	v_div_scale_f32 v40, vcc, 1.0, v38, 1.0
	s_load_dwordx2 s[6:7], s[0:1], 0xb8
	v_fma_f32 v42, -v39, v41, 1.0
	v_fmac_f32_e32 v41, v42, v41
	v_mul_f32_e32 v42, v40, v41
	v_fma_f32 v43, -v39, v42, v40
	v_fmac_f32_e32 v42, v43, v41
	s_lshr_b32 s4, s35, 5
	v_fma_f32 v39, -v39, v42, v40
	s_mulk_i32 s4, 0x4800
	v_div_fmas_f32 v39, v39, v41, v42
	v_lshl_add_u64 v[32:33], v[32:33], 0, s[4:5]
	v_div_fixup_f32 v38, v39, v38, 1.0
	v_lshlrev_b64 v[32:33], 6, v[32:33]
	v_pk_mul_f32 v[16:17], v[16:17], v[38:39] op_sel_hi:[1,0]
	v_pk_mul_f32 v[18:19], v[18:19], v[38:39] op_sel_hi:[1,0]
	s_waitcnt lgkmcnt(0)
	v_lshl_add_u64 v[32:33], s[6:7], 0, v[32:33]
	v_lshl_add_u64 v[32:33], v[32:33], 0, v[192:193]
	s_mov_b32 s4, 0x120000
	v_pk_mul_f32 v[0:1], v[0:1], v[38:39] op_sel_hi:[1,0]
	v_pk_mul_f32 v[2:3], v[2:3], v[38:39] op_sel_hi:[1,0]
	s_waitcnt vmcnt(0)
	v_lshlrev_b32_e32 v40, 16, v36
	v_and_b32_e32 v41, 0xffff0000, v36
	v_lshlrev_b32_e32 v36, 16, v37
	v_and_b32_e32 v37, 0xffff0000, v37
	v_pk_mul_f32 v[16:17], v[16:17], v[40:41]
	v_pk_mul_f32 v[18:19], v[18:19], v[36:37]
	v_cvt_pk_bf16_f32 v16, v16, v17
	v_cvt_pk_bf16_f32 v17, v18, v19
	global_store_dwordx2 v[32:33], v[16:17], off
	s_nop 1
	v_mov_b32_e32 v16, v48
	v_mov_b32_e32 v17, v49
	v_pk_mul_f32 v[18:19], v[20:21], v[38:39] op_sel_hi:[1,0]
	v_pk_mul_f32 v[20:21], v[22:23], v[38:39] op_sel_hi:[1,0]
	s_waitcnt vmcnt(0)
	v_lshlrev_b32_e32 v22, 16, v16
	v_and_b32_e32 v23, 0xffff0000, v16
	v_lshlrev_b32_e32 v16, 16, v17
	v_and_b32_e32 v17, 0xffff0000, v17
	v_pk_mul_f32 v[18:19], v[18:19], v[22:23]
	v_pk_mul_f32 v[16:17], v[20:21], v[16:17]
	v_cvt_pk_bf16_f32 v18, v18, v19
	v_cvt_pk_bf16_f32 v19, v16, v17
	global_store_dwordx2 v[32:33], v[18:19], off offset:16
	s_nop 1
	v_mov_b32_e32 v16, v50
	v_mov_b32_e32 v17, v51
	v_pk_mul_f32 v[18:19], v[24:25], v[38:39] op_sel_hi:[1,0]
	v_pk_mul_f32 v[20:21], v[26:27], v[38:39] op_sel_hi:[1,0]
	s_waitcnt vmcnt(0)
	v_lshlrev_b32_e32 v22, 16, v16
	v_and_b32_e32 v23, 0xffff0000, v16
	v_lshlrev_b32_e32 v16, 16, v17
	v_and_b32_e32 v17, 0xffff0000, v17
	v_pk_mul_f32 v[18:19], v[18:19], v[22:23]
	v_pk_mul_f32 v[16:17], v[20:21], v[16:17]
	v_cvt_pk_bf16_f32 v18, v18, v19
	v_cvt_pk_bf16_f32 v19, v16, v17
	global_store_dwordx2 v[32:33], v[18:19], off offset:32
	s_nop 1
	v_mov_b32_e32 v16, v52
	v_mov_b32_e32 v17, v53
	v_pk_mul_f32 v[18:19], v[28:29], v[38:39] op_sel_hi:[1,0]
	v_pk_mul_f32 v[20:21], v[30:31], v[38:39] op_sel_hi:[1,0]
	s_waitcnt vmcnt(0)
	v_lshlrev_b32_e32 v22, 16, v16
	v_and_b32_e32 v23, 0xffff0000, v16
	v_lshlrev_b32_e32 v16, 16, v17
	v_and_b32_e32 v17, 0xffff0000, v17
	v_pk_mul_f32 v[18:19], v[18:19], v[22:23]
	v_pk_mul_f32 v[16:17], v[20:21], v[16:17]
	v_cvt_pk_bf16_f32 v18, v18, v19
	v_cvt_pk_bf16_f32 v19, v16, v17
	global_store_dwordx2 v[32:33], v[18:19], off offset:48
	s_nop 1
	v_mov_b32_e32 v16, v54
	v_mov_b32_e32 v17, v55
	v_add_co_u32_e32 v18, vcc, s4, v32
	s_mov_b64 s[4:5], 0
	s_nop 0
	v_addc_co_u32_e32 v19, vcc, 0, v33, vcc
	s_waitcnt vmcnt(0)
	v_lshlrev_b32_e32 v20, 16, v16
	v_and_b32_e32 v21, 0xffff0000, v16
	v_lshlrev_b32_e32 v16, 16, v17
	v_and_b32_e32 v17, 0xffff0000, v17
	v_pk_mul_f32 v[0:1], v[0:1], v[20:21]
	v_pk_mul_f32 v[2:3], v[2:3], v[16:17]
	v_cvt_pk_bf16_f32 v0, v0, v1
	v_cvt_pk_bf16_f32 v1, v2, v3
	global_store_dwordx2 v[18:19], v[0:1], off
	s_nop 1
	v_mov_b32_e32 v0, v56
	v_mov_b32_e32 v1, v57
	v_pk_mul_f32 v[2:3], v[4:5], v[38:39] op_sel_hi:[1,0]
	v_pk_mul_f32 v[4:5], v[6:7], v[38:39] op_sel_hi:[1,0]
	s_waitcnt vmcnt(0)
	v_lshlrev_b32_e32 v6, 16, v0
	v_and_b32_e32 v7, 0xffff0000, v0
	v_lshlrev_b32_e32 v0, 16, v1
	v_and_b32_e32 v1, 0xffff0000, v1
	v_pk_mul_f32 v[2:3], v[2:3], v[6:7]
	v_pk_mul_f32 v[0:1], v[4:5], v[0:1]
	v_cvt_pk_bf16_f32 v2, v2, v3
	v_cvt_pk_bf16_f32 v3, v0, v1
	global_store_dwordx2 v[18:19], v[2:3], off offset:16
	s_nop 1
	v_mov_b32_e32 v0, v58
	v_mov_b32_e32 v1, v59
	v_pk_mul_f32 v[2:3], v[8:9], v[38:39] op_sel_hi:[1,0]
	v_pk_mul_f32 v[4:5], v[10:11], v[38:39] op_sel_hi:[1,0]
	s_waitcnt vmcnt(0)
	v_lshlrev_b32_e32 v6, 16, v0
	v_and_b32_e32 v7, 0xffff0000, v0
	v_lshlrev_b32_e32 v0, 16, v1
	v_and_b32_e32 v1, 0xffff0000, v1
	v_pk_mul_f32 v[2:3], v[2:3], v[6:7]
	v_pk_mul_f32 v[0:1], v[4:5], v[0:1]
	v_cvt_pk_bf16_f32 v2, v2, v3
	v_cvt_pk_bf16_f32 v3, v0, v1
	global_store_dwordx2 v[18:19], v[2:3], off offset:32
	s_nop 1
	v_mov_b32_e32 v0, v60
	v_mov_b32_e32 v1, v61
	v_pk_mul_f32 v[2:3], v[12:13], v[38:39] op_sel_hi:[1,0]
	v_pk_mul_f32 v[4:5], v[14:15], v[38:39] op_sel_hi:[1,0]
	s_waitcnt vmcnt(0)
	v_lshlrev_b32_e32 v6, 16, v0
	v_and_b32_e32 v7, 0xffff0000, v0
	v_lshlrev_b32_e32 v0, 16, v1
	v_and_b32_e32 v1, 0xffff0000, v1
	v_pk_mul_f32 v[2:3], v[2:3], v[6:7]
	v_pk_mul_f32 v[0:1], v[4:5], v[0:1]
	v_cvt_pk_bf16_f32 v2, v2, v3
	v_cvt_pk_bf16_f32 v3, v0, v1
	global_store_dwordx2 v[18:19], v[2:3], off offset:48
